# ffup ConvGLU epilogue re-emitted with packed f32 ops on element pairs (same per-element operations), image rows read one block ahead
# speedup vs baseline: 1.0182x; 1.0030x over previous
; DI float bf2f(u16 h) { return __uint_as_float(((unsigned)h) << 16); }
; DI float gelu_tanh(float x) { float u = 0.7978845608028654f * (x + 0.044715f * x * x * x); return x * sigmoidf_(2.f * u); }
; DI void ffup_tile(const Params& p, int l, int mt, int nt, char* smem) {
;     ...
;     const u16* img = (const u16*)smem + (wr * 128 + fq * 4) * IMG_LD + wc * 64 + fr;
; #pragma unroll
;     for (int n = 0; n < 4; ++n) {
;       const int col = col0 + wc * 64 + n * 16 + fr;
;       const float* cw = p.in[30] + (size_t)l * 3 * DFF + col;
;       const float w0 = cw[0], w1 = cw[DFF], w2 = cw[2 * DFF], cb = p.in[31][(size_t)l * DFF + col];
; #pragma unroll
;       for (int m = 0; m < 8; ++m) {
;         if ((m & 1) == 0) asm volatile("" ::: "memory");
;         const int t = (row0 + wr * 128 + m * 16 + fq * 4) & 8191;
;         float g[6];
; #pragma unroll
;         for (int d = 0; d < 6; ++d) { const float gv = bf2f(img[(m * 16 + d) * IMG_LD + n * 16]); g[d] = (d >= 2 || t - 2 + d >= 0) ? gv : 0.f; }
; #pragma unroll
;         for (int j = 0; j < 4; ++j) acc[m][n][j] *= gelu_tanh(cb + w0 * g[j] + w1 * g[j + 1] + w2 * g[j + 2]);
;       }
.LBB0_2354:
	v_and_b32_e32 v0, 0xc0, v132
	v_and_b32_e32 v1, 15, v132
	v_ashrrev_i32_e32 v133, 1, v132
	v_lshrrev_b32_e32 v2, 2, v132
	v_and_b32_e32 v132, 12, v2
	s_mov_b32 s5, 0xfffff80
	v_lshlrev_b32_e32 v134, 1, v0
	v_lshlrev_b32_e32 v135, 1, v1
	v_or3_b32 v0, v0, s46, v1
	v_add_u32_e32 v1, s13, v133
	s_movk_i32 s4, 0x1f80
	v_and_or_b32 v2, v133, s5, v132
	v_and_or_b32 v142, v1, s4, v132
	v_ashrrev_i32_e32 v1, 31, v0
	v_mul_lo_u32 v2, v2, s3
	v_lshlrev_b64 v[0:1], 2, v[0:1]
	v_add_u32_e32 v2, 16, v2
	v_lshl_add_u64 v[132:133], s[40:41], 0, v[0:1]
	s_movk_i32 s4, 0x2000
	v_add3_u32 v2, v2, v134, v135
	v_add_co_u32_e32 v134, vcc, s4, v132
	s_movk_i32 s4, 0x5000
	s_nop 0
	v_addc_co_u32_e32 v135, vcc, 0, v133, vcc
	v_lshl_add_u64 v[0:1], s[44:45], 0, v[0:1]
	v_add_co_u32_e32 v136, vcc, s4, v132
	s_nop 1
	v_addc_co_u32_e32 v137, vcc, 0, v133, vcc
	global_load_dword v138, v[132:133], off
	global_load_dword v139, v[134:135], off offset:3072
	global_load_dword v140, v[136:137], off offset:2048
	global_load_dword v141, v[0:1], off
	global_load_dword v150, v[132:133], off offset:64
	global_load_dword v151, v[134:135], off offset:3136
	global_load_dword v152, v[136:137], off offset:2112
	global_load_dword v153, v[0:1], off offset:64
	global_load_dword v154, v[132:133], off offset:128
	global_load_dword v155, v[134:135], off offset:3200
	global_load_dword v156, v[136:137], off offset:2176
	global_load_dword v157, v[0:1], off offset:128
	global_load_dword v158, v[132:133], off offset:192
	global_load_dword v159, v[134:135], off offset:3264
	global_load_dword v160, v[136:137], off offset:2240
	global_load_dword v161, v[0:1], off offset:192
	s_waitcnt lgkmcnt(0)
	s_barrier
	v_cmp_eq_u32_e32 vcc, 0, v142
	s_add_u32 s4, s76, s38
	v_mov_b32_e32 v176, 0x3d372713
	v_mov_b32_e32 v177, 0x3d372713
	v_mov_b32_e32 v178, 0x3f4c422a
	v_mov_b32_e32 v179, 0x3f4c422a
	v_mov_b32_e32 v180, 0xbfb8aa3b
	v_mov_b32_e32 v181, 0xbfb8aa3b
	v_mov_b32_e32 v182, 1.0
	v_mov_b32_e32 v183, 1.0
	ds_read_u16 v214, v2
	ds_read_u16 v215, v2 offset:528
	ds_read_u16 v216, v2 offset:1056
	ds_read_u16 v217, v2 offset:1584
	ds_read_u16 v218, v2 offset:2112
	ds_read_u16 v219, v2 offset:2640
	ds_read_u16 v226, v2 offset:8448
	ds_read_u16 v227, v2 offset:8976
	ds_read_u16 v228, v2 offset:9504
	ds_read_u16 v229, v2 offset:10032
	ds_read_u16 v230, v2 offset:10560
	ds_read_u16 v231, v2 offset:11088
	s_waitcnt lgkmcnt(6)
	s_waitcnt vmcnt(12)
	v_mov_b32_e32 v162, v138
	v_mov_b32_e32 v163, v138
	v_mov_b32_e32 v164, v139
	v_mov_b32_e32 v165, v139
	v_mov_b32_e32 v166, v140
	v_mov_b32_e32 v167, v140
	v_mov_b32_e32 v168, v141
	v_mov_b32_e32 v169, v141
	v_lshlrev_b32_e32 v214, 16, v214
	v_lshlrev_b32_e32 v215, 16, v215
	v_lshlrev_b32_e32 v216, 16, v216
	v_lshlrev_b32_e32 v217, 16, v217
	v_lshlrev_b32_e32 v218, 16, v218
	v_lshlrev_b32_e32 v219, 16, v219
	v_cndmask_b32_e64 v214, v214, 0, vcc
	v_cndmask_b32_e64 v215, v215, 0, vcc
	v_mov_b32_e32 v220, v215
	v_mov_b32_e32 v221, v216
	v_mov_b32_e32 v222, v217
	v_mov_b32_e32 v223, v218
	v_mov_b32_e32 v224, v219
	v_pk_fma_f32 v[238:239], v[162:163], v[214:215], v[168:169]
	v_pk_fma_f32 v[240:241], v[162:163], v[216:217], v[168:169]
	v_pk_fma_f32 v[238:239], v[164:165], v[220:221], v[238:239]
	v_pk_fma_f32 v[240:241], v[164:165], v[222:223], v[240:241]
	v_pk_fma_f32 v[238:239], v[166:167], v[216:217], v[238:239]
	v_pk_fma_f32 v[240:241], v[166:167], v[218:219], v[240:241]
	v_pk_mul_f32 v[242:243], v[176:177], v[238:239]
	v_pk_mul_f32 v[244:245], v[176:177], v[240:241]
	v_pk_mul_f32 v[242:243], v[238:239], v[242:243]
	v_pk_mul_f32 v[244:245], v[240:241], v[244:245]
	v_pk_fma_f32 v[242:243], v[238:239], v[242:243], v[238:239]
	v_pk_fma_f32 v[244:245], v[240:241], v[244:245], v[240:241]
	v_pk_mul_f32 v[242:243], v[178:179], v[242:243]
	v_pk_mul_f32 v[244:245], v[178:179], v[244:245]
	v_pk_add_f32 v[242:243], v[242:243], v[242:243]
	v_pk_add_f32 v[244:245], v[244:245], v[244:245]
	v_pk_mul_f32 v[242:243], v[180:181], v[242:243]
	v_pk_mul_f32 v[244:245], v[180:181], v[244:245]
	v_exp_f32_e32 v242, v242
	v_exp_f32_e32 v243, v243
	v_exp_f32_e32 v244, v244
	v_exp_f32_e32 v245, v245
	v_pk_add_f32 v[242:243], v[182:183], v[242:243]
	v_pk_add_f32 v[244:245], v[182:183], v[244:245]
	v_rcp_f32_e32 v242, v242
	v_rcp_f32_e32 v243, v243
	v_rcp_f32_e32 v244, v244
	v_rcp_f32_e32 v245, v245
	v_pk_mul_f32 v[238:239], v[238:239], v[242:243]
	v_pk_mul_f32 v[240:241], v[240:241], v[244:245]
	v_pk_mul_f32 v[128:129], v[128:129], v[238:239]
	v_pk_mul_f32 v[130:131], v[130:131], v[240:241]
	ds_read_u16 v214, v2 offset:16896
	ds_read_u16 v215, v2 offset:17424
	ds_read_u16 v216, v2 offset:17952
	ds_read_u16 v217, v2 offset:18480
	ds_read_u16 v218, v2 offset:19008
	ds_read_u16 v219, v2 offset:19536
	s_waitcnt lgkmcnt(6)
; DI float bf2f(u16 h) { return __uint_as_float(((unsigned)h) << 16); }
; DI float gelu_tanh(float x) { float u = 0.7978845608028654f * (x + 0.044715f * x * x * x); return x * sigmoidf_(2.f * u); }
; DI void ffup_tile(const Params& p, int l, int mt, int nt, char* smem) {
;     ...
;     const u16* img = (const u16*)smem + (wr * 128 + fq * 4) * IMG_LD + wc * 64 + fr;
; #pragma unroll
;     for (int n = 0; n < 4; ++n) {
;       const int col = col0 + wc * 64 + n * 16 + fr;
;       const float* cw = p.in[30] + (size_t)l * 3 * DFF + col;
;       const float w0 = cw[0], w1 = cw[DFF], w2 = cw[2 * DFF], cb = p.in[31][(size_t)l * DFF + col];
; #pragma unroll
;       for (int m = 0; m < 8; ++m) {
;         if ((m & 1) == 0) asm volatile("" ::: "memory");
;         const int t = (row0 + wr * 128 + m * 16 + fq * 4) & 8191;
;         float g[6];
; #pragma unroll
;         for (int d = 0; d < 6; ++d) { const float gv = bf2f(img[(m * 16 + d) * IMG_LD + n * 16]); g[d] = (d >= 2 || t - 2 + d >= 0) ? gv : 0.f; }
; #pragma unroll
;         for (int j = 0; j < 4; ++j) acc[m][n][j] *= gelu_tanh(cb + w0 * g[j] + w1 * g[j + 1] + w2 * g[j + 2]);
;       }
	v_lshlrev_b32_e32 v226, 16, v226
	v_lshlrev_b32_e32 v227, 16, v227
	v_lshlrev_b32_e32 v228, 16, v228
	v_lshlrev_b32_e32 v229, 16, v229
	v_lshlrev_b32_e32 v230, 16, v230
	v_lshlrev_b32_e32 v231, 16, v231
	v_mov_b32_e32 v232, v227
	v_mov_b32_e32 v233, v228
	v_mov_b32_e32 v234, v229
	v_mov_b32_e32 v235, v230
	v_mov_b32_e32 v236, v231
	v_pk_fma_f32 v[238:239], v[162:163], v[226:227], v[168:169]
	v_pk_fma_f32 v[240:241], v[162:163], v[228:229], v[168:169]
	v_pk_fma_f32 v[238:239], v[164:165], v[232:233], v[238:239]
	v_pk_fma_f32 v[240:241], v[164:165], v[234:235], v[240:241]
	v_pk_fma_f32 v[238:239], v[166:167], v[228:229], v[238:239]
	v_pk_fma_f32 v[240:241], v[166:167], v[230:231], v[240:241]
	v_pk_mul_f32 v[242:243], v[176:177], v[238:239]
	v_pk_mul_f32 v[244:245], v[176:177], v[240:241]
	v_pk_mul_f32 v[242:243], v[238:239], v[242:243]
	v_pk_mul_f32 v[244:245], v[240:241], v[244:245]
	v_pk_fma_f32 v[242:243], v[238:239], v[242:243], v[238:239]
	v_pk_fma_f32 v[244:245], v[240:241], v[244:245], v[240:241]
	v_pk_mul_f32 v[242:243], v[178:179], v[242:243]
	v_pk_mul_f32 v[244:245], v[178:179], v[244:245]
	v_pk_add_f32 v[242:243], v[242:243], v[242:243]
	v_pk_add_f32 v[244:245], v[244:245], v[244:245]
	v_pk_mul_f32 v[242:243], v[180:181], v[242:243]
	v_pk_mul_f32 v[244:245], v[180:181], v[244:245]
	v_exp_f32_e32 v242, v242
	v_exp_f32_e32 v243, v243
	v_exp_f32_e32 v244, v244
	v_exp_f32_e32 v245, v245
	v_pk_add_f32 v[242:243], v[182:183], v[242:243]
	v_pk_add_f32 v[244:245], v[182:183], v[244:245]
	v_rcp_f32_e32 v242, v242
	v_rcp_f32_e32 v243, v243
	v_rcp_f32_e32 v244, v244
	v_rcp_f32_e32 v245, v245
	v_pk_mul_f32 v[238:239], v[238:239], v[242:243]
	v_pk_mul_f32 v[240:241], v[240:241], v[244:245]
	v_pk_mul_f32 v[124:125], v[124:125], v[238:239]
	v_pk_mul_f32 v[126:127], v[126:127], v[240:241]
	ds_read_u16 v226, v2 offset:25344
	ds_read_u16 v227, v2 offset:25872
	ds_read_u16 v228, v2 offset:26400
	ds_read_u16 v229, v2 offset:26928
	ds_read_u16 v230, v2 offset:27456
	ds_read_u16 v231, v2 offset:27984
	s_waitcnt lgkmcnt(6)
	v_lshlrev_b32_e32 v214, 16, v214
	v_lshlrev_b32_e32 v215, 16, v215
	v_lshlrev_b32_e32 v216, 16, v216
	v_lshlrev_b32_e32 v217, 16, v217
	v_lshlrev_b32_e32 v218, 16, v218
	v_lshlrev_b32_e32 v219, 16, v219
	v_mov_b32_e32 v220, v215
	v_mov_b32_e32 v221, v216
	v_mov_b32_e32 v222, v217
	v_mov_b32_e32 v223, v218
	v_mov_b32_e32 v224, v219
	v_pk_fma_f32 v[238:239], v[162:163], v[214:215], v[168:169]
	v_pk_fma_f32 v[240:241], v[162:163], v[216:217], v[168:169]
	v_pk_fma_f32 v[238:239], v[164:165], v[220:221], v[238:239]
	v_pk_fma_f32 v[240:241], v[164:165], v[222:223], v[240:241]
	v_pk_fma_f32 v[238:239], v[166:167], v[216:217], v[238:239]
	v_pk_fma_f32 v[240:241], v[166:167], v[218:219], v[240:241]
	v_pk_mul_f32 v[242:243], v[176:177], v[238:239]
	v_pk_mul_f32 v[244:245], v[176:177], v[240:241]
	v_pk_mul_f32 v[242:243], v[238:239], v[242:243]
	v_pk_mul_f32 v[244:245], v[240:241], v[244:245]
	v_pk_fma_f32 v[242:243], v[238:239], v[242:243], v[238:239]
	v_pk_fma_f32 v[244:245], v[240:241], v[244:245], v[240:241]
	v_pk_mul_f32 v[242:243], v[178:179], v[242:243]
	v_pk_mul_f32 v[244:245], v[178:179], v[244:245]
	v_pk_add_f32 v[242:243], v[242:243], v[242:243]
	v_pk_add_f32 v[244:245], v[244:245], v[244:245]
	v_pk_mul_f32 v[242:243], v[180:181], v[242:243]
	v_pk_mul_f32 v[244:245], v[180:181], v[244:245]
	v_exp_f32_e32 v242, v242
	v_exp_f32_e32 v243, v243
	v_exp_f32_e32 v244, v244
	v_exp_f32_e32 v245, v245
	v_pk_add_f32 v[242:243], v[182:183], v[242:243]
	v_pk_add_f32 v[244:245], v[182:183], v[244:245]
	v_rcp_f32_e32 v242, v242
	v_rcp_f32_e32 v243, v243
	v_rcp_f32_e32 v244, v244
	v_rcp_f32_e32 v245, v245
	v_pk_mul_f32 v[238:239], v[238:239], v[242:243]
	v_pk_mul_f32 v[240:241], v[240:241], v[244:245]
	v_pk_mul_f32 v[120:121], v[120:121], v[238:239]
	v_pk_mul_f32 v[122:123], v[122:123], v[240:241]
	ds_read_u16 v214, v2 offset:33792
	ds_read_u16 v215, v2 offset:34320
	ds_read_u16 v216, v2 offset:34848
	ds_read_u16 v217, v2 offset:35376
	ds_read_u16 v218, v2 offset:35904
	ds_read_u16 v219, v2 offset:36432
	s_waitcnt lgkmcnt(6)
	v_lshlrev_b32_e32 v226, 16, v226
	v_lshlrev_b32_e32 v227, 16, v227
	v_lshlrev_b32_e32 v228, 16, v228
	v_lshlrev_b32_e32 v229, 16, v229
	v_lshlrev_b32_e32 v230, 16, v230
	v_lshlrev_b32_e32 v231, 16, v231
	v_mov_b32_e32 v232, v227
	v_mov_b32_e32 v233, v228
	v_mov_b32_e32 v234, v229
	v_mov_b32_e32 v235, v230
	v_mov_b32_e32 v236, v231
	v_pk_fma_f32 v[238:239], v[162:163], v[226:227], v[168:169]
	v_pk_fma_f32 v[240:241], v[162:163], v[228:229], v[168:169]
	v_pk_fma_f32 v[238:239], v[164:165], v[232:233], v[238:239]
	v_pk_fma_f32 v[240:241], v[164:165], v[234:235], v[240:241]
	v_pk_fma_f32 v[238:239], v[166:167], v[228:229], v[238:239]
	v_pk_fma_f32 v[240:241], v[166:167], v[230:231], v[240:241]
	v_pk_mul_f32 v[242:243], v[176:177], v[238:239]
	v_pk_mul_f32 v[244:245], v[176:177], v[240:241]
	v_pk_mul_f32 v[242:243], v[238:239], v[242:243]
	v_pk_mul_f32 v[244:245], v[240:241], v[244:245]
	v_pk_fma_f32 v[242:243], v[238:239], v[242:243], v[238:239]
	v_pk_fma_f32 v[244:245], v[240:241], v[244:245], v[240:241]
	v_pk_mul_f32 v[242:243], v[178:179], v[242:243]
	v_pk_mul_f32 v[244:245], v[178:179], v[244:245]
	v_pk_add_f32 v[242:243], v[242:243], v[242:243]
	v_pk_add_f32 v[244:245], v[244:245], v[244:245]
	v_pk_mul_f32 v[242:243], v[180:181], v[242:243]
	v_pk_mul_f32 v[244:245], v[180:181], v[244:245]
	v_exp_f32_e32 v242, v242
	v_exp_f32_e32 v243, v243
	v_exp_f32_e32 v244, v244
	v_exp_f32_e32 v245, v245
	v_pk_add_f32 v[242:243], v[182:183], v[242:243]
	v_pk_add_f32 v[244:245], v[182:183], v[244:245]
	v_rcp_f32_e32 v242, v242
	v_rcp_f32_e32 v243, v243
	v_rcp_f32_e32 v244, v244
	v_rcp_f32_e32 v245, v245
	v_pk_mul_f32 v[238:239], v[238:239], v[242:243]
	v_pk_mul_f32 v[240:241], v[240:241], v[244:245]
	v_pk_mul_f32 v[116:117], v[116:117], v[238:239]
	v_pk_mul_f32 v[118:119], v[118:119], v[240:241]
	ds_read_u16 v226, v2 offset:42240
	ds_read_u16 v227, v2 offset:42768
	ds_read_u16 v228, v2 offset:43296
	ds_read_u16 v229, v2 offset:43824
	ds_read_u16 v230, v2 offset:44352
	ds_read_u16 v231, v2 offset:44880
	s_waitcnt lgkmcnt(6)
; DI float bf2f(u16 h) { return __uint_as_float(((unsigned)h) << 16); }
; DI float gelu_tanh(float x) { float u = 0.7978845608028654f * (x + 0.044715f * x * x * x); return x * sigmoidf_(2.f * u); }
; DI void ffup_tile(const Params& p, int l, int mt, int nt, char* smem) {
;     ...
;     const u16* img = (const u16*)smem + (wr * 128 + fq * 4) * IMG_LD + wc * 64 + fr;
; #pragma unroll
;     for (int n = 0; n < 4; ++n) {
;       const int col = col0 + wc * 64 + n * 16 + fr;
;       const float* cw = p.in[30] + (size_t)l * 3 * DFF + col;
;       const float w0 = cw[0], w1 = cw[DFF], w2 = cw[2 * DFF], cb = p.in[31][(size_t)l * DFF + col];
; #pragma unroll
;       for (int m = 0; m < 8; ++m) {
;         if ((m & 1) == 0) asm volatile("" ::: "memory");
;         const int t = (row0 + wr * 128 + m * 16 + fq * 4) & 8191;
;         float g[6];
; #pragma unroll
;         for (int d = 0; d < 6; ++d) { const float gv = bf2f(img[(m * 16 + d) * IMG_LD + n * 16]); g[d] = (d >= 2 || t - 2 + d >= 0) ? gv : 0.f; }
; #pragma unroll
;         for (int j = 0; j < 4; ++j) acc[m][n][j] *= gelu_tanh(cb + w0 * g[j] + w1 * g[j + 1] + w2 * g[j + 2]);
;       }
	v_lshlrev_b32_e32 v214, 16, v214
	v_lshlrev_b32_e32 v215, 16, v215
	v_lshlrev_b32_e32 v216, 16, v216
	v_lshlrev_b32_e32 v217, 16, v217
	v_lshlrev_b32_e32 v218, 16, v218
	v_lshlrev_b32_e32 v219, 16, v219
	v_mov_b32_e32 v220, v215
	v_mov_b32_e32 v221, v216
	v_mov_b32_e32 v222, v217
	v_mov_b32_e32 v223, v218
	v_mov_b32_e32 v224, v219
	v_pk_fma_f32 v[238:239], v[162:163], v[214:215], v[168:169]
	v_pk_fma_f32 v[240:241], v[162:163], v[216:217], v[168:169]
	v_pk_fma_f32 v[238:239], v[164:165], v[220:221], v[238:239]
	v_pk_fma_f32 v[240:241], v[164:165], v[222:223], v[240:241]
	v_pk_fma_f32 v[238:239], v[166:167], v[216:217], v[238:239]
	v_pk_fma_f32 v[240:241], v[166:167], v[218:219], v[240:241]
	v_pk_mul_f32 v[242:243], v[176:177], v[238:239]
	v_pk_mul_f32 v[244:245], v[176:177], v[240:241]
	v_pk_mul_f32 v[242:243], v[238:239], v[242:243]
	v_pk_mul_f32 v[244:245], v[240:241], v[244:245]
	v_pk_fma_f32 v[242:243], v[238:239], v[242:243], v[238:239]
	v_pk_fma_f32 v[244:245], v[240:241], v[244:245], v[240:241]
	v_pk_mul_f32 v[242:243], v[178:179], v[242:243]
	v_pk_mul_f32 v[244:245], v[178:179], v[244:245]
	v_pk_add_f32 v[242:243], v[242:243], v[242:243]
	v_pk_add_f32 v[244:245], v[244:245], v[244:245]
	v_pk_mul_f32 v[242:243], v[180:181], v[242:243]
	v_pk_mul_f32 v[244:245], v[180:181], v[244:245]
	v_exp_f32_e32 v242, v242
	v_exp_f32_e32 v243, v243
	v_exp_f32_e32 v244, v244
	v_exp_f32_e32 v245, v245
	v_pk_add_f32 v[242:243], v[182:183], v[242:243]
	v_pk_add_f32 v[244:245], v[182:183], v[244:245]
	v_rcp_f32_e32 v242, v242
	v_rcp_f32_e32 v243, v243
	v_rcp_f32_e32 v244, v244
	v_rcp_f32_e32 v245, v245
	v_pk_mul_f32 v[238:239], v[238:239], v[242:243]
	v_pk_mul_f32 v[240:241], v[240:241], v[244:245]
	v_pk_mul_f32 v[112:113], v[112:113], v[238:239]
	v_pk_mul_f32 v[114:115], v[114:115], v[240:241]
	ds_read_u16 v214, v2 offset:50688
	ds_read_u16 v215, v2 offset:51216
	ds_read_u16 v216, v2 offset:51744
	ds_read_u16 v217, v2 offset:52272
	ds_read_u16 v218, v2 offset:52800
	ds_read_u16 v219, v2 offset:53328
	s_waitcnt lgkmcnt(6)
	v_lshlrev_b32_e32 v226, 16, v226
	v_lshlrev_b32_e32 v227, 16, v227
	v_lshlrev_b32_e32 v228, 16, v228
	v_lshlrev_b32_e32 v229, 16, v229
	v_lshlrev_b32_e32 v230, 16, v230
	v_lshlrev_b32_e32 v231, 16, v231
	v_mov_b32_e32 v232, v227
	v_mov_b32_e32 v233, v228
	v_mov_b32_e32 v234, v229
	v_mov_b32_e32 v235, v230
	v_mov_b32_e32 v236, v231
	v_pk_fma_f32 v[238:239], v[162:163], v[226:227], v[168:169]
	v_pk_fma_f32 v[240:241], v[162:163], v[228:229], v[168:169]
	v_pk_fma_f32 v[238:239], v[164:165], v[232:233], v[238:239]
	v_pk_fma_f32 v[240:241], v[164:165], v[234:235], v[240:241]
	v_pk_fma_f32 v[238:239], v[166:167], v[228:229], v[238:239]
	v_pk_fma_f32 v[240:241], v[166:167], v[230:231], v[240:241]
	v_pk_mul_f32 v[242:243], v[176:177], v[238:239]
	v_pk_mul_f32 v[244:245], v[176:177], v[240:241]
	v_pk_mul_f32 v[242:243], v[238:239], v[242:243]
	v_pk_mul_f32 v[244:245], v[240:241], v[244:245]
	v_pk_fma_f32 v[242:243], v[238:239], v[242:243], v[238:239]
	v_pk_fma_f32 v[244:245], v[240:241], v[244:245], v[240:241]
	v_pk_mul_f32 v[242:243], v[178:179], v[242:243]
	v_pk_mul_f32 v[244:245], v[178:179], v[244:245]
	v_pk_add_f32 v[242:243], v[242:243], v[242:243]
	v_pk_add_f32 v[244:245], v[244:245], v[244:245]
	v_pk_mul_f32 v[242:243], v[180:181], v[242:243]
	v_pk_mul_f32 v[244:245], v[180:181], v[244:245]
	v_exp_f32_e32 v242, v242
	v_exp_f32_e32 v243, v243
	v_exp_f32_e32 v244, v244
	v_exp_f32_e32 v245, v245
	v_pk_add_f32 v[242:243], v[182:183], v[242:243]
	v_pk_add_f32 v[244:245], v[182:183], v[244:245]
	v_rcp_f32_e32 v242, v242
	v_rcp_f32_e32 v243, v243
	v_rcp_f32_e32 v244, v244
	v_rcp_f32_e32 v245, v245
	v_pk_mul_f32 v[238:239], v[238:239], v[242:243]
	v_pk_mul_f32 v[240:241], v[240:241], v[244:245]
	v_pk_mul_f32 v[108:109], v[108:109], v[238:239]
	v_pk_mul_f32 v[110:111], v[110:111], v[240:241]
	ds_read_u16 v226, v2 offset:59136
	ds_read_u16 v227, v2 offset:59664
	ds_read_u16 v228, v2 offset:60192
	ds_read_u16 v229, v2 offset:60720
	ds_read_u16 v230, v2 offset:61248
	ds_read_u16 v231, v2 offset:61776
	s_waitcnt lgkmcnt(6)
	v_lshlrev_b32_e32 v214, 16, v214
	v_lshlrev_b32_e32 v215, 16, v215
	v_lshlrev_b32_e32 v216, 16, v216
	v_lshlrev_b32_e32 v217, 16, v217
	v_lshlrev_b32_e32 v218, 16, v218
	v_lshlrev_b32_e32 v219, 16, v219
	v_mov_b32_e32 v220, v215
	v_mov_b32_e32 v221, v216
	v_mov_b32_e32 v222, v217
	v_mov_b32_e32 v223, v218
	v_mov_b32_e32 v224, v219
	v_pk_fma_f32 v[238:239], v[162:163], v[214:215], v[168:169]
	v_pk_fma_f32 v[240:241], v[162:163], v[216:217], v[168:169]
	v_pk_fma_f32 v[238:239], v[164:165], v[220:221], v[238:239]
	v_pk_fma_f32 v[240:241], v[164:165], v[222:223], v[240:241]
	v_pk_fma_f32 v[238:239], v[166:167], v[216:217], v[238:239]
	v_pk_fma_f32 v[240:241], v[166:167], v[218:219], v[240:241]
	v_pk_mul_f32 v[242:243], v[176:177], v[238:239]
	v_pk_mul_f32 v[244:245], v[176:177], v[240:241]
	v_pk_mul_f32 v[242:243], v[238:239], v[242:243]
	v_pk_mul_f32 v[244:245], v[240:241], v[244:245]
	v_pk_fma_f32 v[242:243], v[238:239], v[242:243], v[238:239]
	v_pk_fma_f32 v[244:245], v[240:241], v[244:245], v[240:241]
	v_pk_mul_f32 v[242:243], v[178:179], v[242:243]
	v_pk_mul_f32 v[244:245], v[178:179], v[244:245]
	v_pk_add_f32 v[242:243], v[242:243], v[242:243]
	v_pk_add_f32 v[244:245], v[244:245], v[244:245]
	v_pk_mul_f32 v[242:243], v[180:181], v[242:243]
	v_pk_mul_f32 v[244:245], v[180:181], v[244:245]
	v_exp_f32_e32 v242, v242
	v_exp_f32_e32 v243, v243
	v_exp_f32_e32 v244, v244
	v_exp_f32_e32 v245, v245
	v_pk_add_f32 v[242:243], v[182:183], v[242:243]
	v_pk_add_f32 v[244:245], v[182:183], v[244:245]
	v_rcp_f32_e32 v242, v242
	v_rcp_f32_e32 v243, v243
	v_rcp_f32_e32 v244, v244
	v_rcp_f32_e32 v245, v245
	v_pk_mul_f32 v[238:239], v[238:239], v[242:243]
	v_pk_mul_f32 v[240:241], v[240:241], v[244:245]
	v_pk_mul_f32 v[104:105], v[104:105], v[238:239]
	v_pk_mul_f32 v[106:107], v[106:107], v[240:241]
	ds_read_u16 v214, v2 offset:32
	ds_read_u16 v215, v2 offset:560
	ds_read_u16 v216, v2 offset:1088
	ds_read_u16 v217, v2 offset:1616
	ds_read_u16 v218, v2 offset:2144
	ds_read_u16 v219, v2 offset:2672
	s_waitcnt lgkmcnt(6)
; DI float bf2f(u16 h) { return __uint_as_float(((unsigned)h) << 16); }
; DI float gelu_tanh(float x) { float u = 0.7978845608028654f * (x + 0.044715f * x * x * x); return x * sigmoidf_(2.f * u); }
; DI void ffup_tile(const Params& p, int l, int mt, int nt, char* smem) {
;     ...
;     const u16* img = (const u16*)smem + (wr * 128 + fq * 4) * IMG_LD + wc * 64 + fr;
; #pragma unroll
;     for (int n = 0; n < 4; ++n) {
;       const int col = col0 + wc * 64 + n * 16 + fr;
;       const float* cw = p.in[30] + (size_t)l * 3 * DFF + col;
;       const float w0 = cw[0], w1 = cw[DFF], w2 = cw[2 * DFF], cb = p.in[31][(size_t)l * DFF + col];
; #pragma unroll
;       for (int m = 0; m < 8; ++m) {
;         if ((m & 1) == 0) asm volatile("" ::: "memory");
;         const int t = (row0 + wr * 128 + m * 16 + fq * 4) & 8191;
;         float g[6];
; #pragma unroll
;         for (int d = 0; d < 6; ++d) { const float gv = bf2f(img[(m * 16 + d) * IMG_LD + n * 16]); g[d] = (d >= 2 || t - 2 + d >= 0) ? gv : 0.f; }
; #pragma unroll
;         for (int j = 0; j < 4; ++j) acc[m][n][j] *= gelu_tanh(cb + w0 * g[j] + w1 * g[j + 1] + w2 * g[j + 2]);
;       }
	v_lshlrev_b32_e32 v226, 16, v226
	v_lshlrev_b32_e32 v227, 16, v227
	v_lshlrev_b32_e32 v228, 16, v228
	v_lshlrev_b32_e32 v229, 16, v229
	v_lshlrev_b32_e32 v230, 16, v230
	v_lshlrev_b32_e32 v231, 16, v231
	v_mov_b32_e32 v232, v227
	v_mov_b32_e32 v233, v228
	v_mov_b32_e32 v234, v229
	v_mov_b32_e32 v235, v230
	v_mov_b32_e32 v236, v231
	v_pk_fma_f32 v[238:239], v[162:163], v[226:227], v[168:169]
	v_pk_fma_f32 v[240:241], v[162:163], v[228:229], v[168:169]
	v_pk_fma_f32 v[238:239], v[164:165], v[232:233], v[238:239]
	v_pk_fma_f32 v[240:241], v[164:165], v[234:235], v[240:241]
	v_pk_fma_f32 v[238:239], v[166:167], v[228:229], v[238:239]
	v_pk_fma_f32 v[240:241], v[166:167], v[230:231], v[240:241]
	v_pk_mul_f32 v[242:243], v[176:177], v[238:239]
	v_pk_mul_f32 v[244:245], v[176:177], v[240:241]
	v_pk_mul_f32 v[242:243], v[238:239], v[242:243]
	v_pk_mul_f32 v[244:245], v[240:241], v[244:245]
	v_pk_fma_f32 v[242:243], v[238:239], v[242:243], v[238:239]
	v_pk_fma_f32 v[244:245], v[240:241], v[244:245], v[240:241]
	v_pk_mul_f32 v[242:243], v[178:179], v[242:243]
	v_pk_mul_f32 v[244:245], v[178:179], v[244:245]
	v_pk_add_f32 v[242:243], v[242:243], v[242:243]
	v_pk_add_f32 v[244:245], v[244:245], v[244:245]
	v_pk_mul_f32 v[242:243], v[180:181], v[242:243]
	v_pk_mul_f32 v[244:245], v[180:181], v[244:245]
	v_exp_f32_e32 v242, v242
	v_exp_f32_e32 v243, v243
	v_exp_f32_e32 v244, v244
	v_exp_f32_e32 v245, v245
	v_pk_add_f32 v[242:243], v[182:183], v[242:243]
	v_pk_add_f32 v[244:245], v[182:183], v[244:245]
	v_rcp_f32_e32 v242, v242
	v_rcp_f32_e32 v243, v243
	v_rcp_f32_e32 v244, v244
	v_rcp_f32_e32 v245, v245
	v_pk_mul_f32 v[238:239], v[238:239], v[242:243]
	v_pk_mul_f32 v[240:241], v[240:241], v[244:245]
	v_pk_mul_f32 v[100:101], v[100:101], v[238:239]
	v_pk_mul_f32 v[102:103], v[102:103], v[240:241]
	ds_read_u16 v226, v2 offset:8480
	ds_read_u16 v227, v2 offset:9008
	ds_read_u16 v228, v2 offset:9536
	ds_read_u16 v229, v2 offset:10064
	ds_read_u16 v230, v2 offset:10592
	ds_read_u16 v231, v2 offset:11120
	s_waitcnt lgkmcnt(6)
	s_waitcnt vmcnt(8)
	v_mov_b32_e32 v162, v150
	v_mov_b32_e32 v163, v150
	v_mov_b32_e32 v164, v151
	v_mov_b32_e32 v165, v151
	v_mov_b32_e32 v166, v152
	v_mov_b32_e32 v167, v152
	v_mov_b32_e32 v168, v153
	v_mov_b32_e32 v169, v153
	v_lshlrev_b32_e32 v214, 16, v214
	v_lshlrev_b32_e32 v215, 16, v215
	v_lshlrev_b32_e32 v216, 16, v216
	v_lshlrev_b32_e32 v217, 16, v217
	v_lshlrev_b32_e32 v218, 16, v218
	v_lshlrev_b32_e32 v219, 16, v219
	v_cndmask_b32_e64 v214, v214, 0, vcc
	v_cndmask_b32_e64 v215, v215, 0, vcc
	v_mov_b32_e32 v220, v215
	v_mov_b32_e32 v221, v216
	v_mov_b32_e32 v222, v217
	v_mov_b32_e32 v223, v218
	v_mov_b32_e32 v224, v219
	v_pk_fma_f32 v[238:239], v[162:163], v[214:215], v[168:169]
	v_pk_fma_f32 v[240:241], v[162:163], v[216:217], v[168:169]
	v_pk_fma_f32 v[238:239], v[164:165], v[220:221], v[238:239]
	v_pk_fma_f32 v[240:241], v[164:165], v[222:223], v[240:241]
	v_pk_fma_f32 v[238:239], v[166:167], v[216:217], v[238:239]
	v_pk_fma_f32 v[240:241], v[166:167], v[218:219], v[240:241]
	v_pk_mul_f32 v[242:243], v[176:177], v[238:239]
	v_pk_mul_f32 v[244:245], v[176:177], v[240:241]
	v_pk_mul_f32 v[242:243], v[238:239], v[242:243]
	v_pk_mul_f32 v[244:245], v[240:241], v[244:245]
	v_pk_fma_f32 v[242:243], v[238:239], v[242:243], v[238:239]
	v_pk_fma_f32 v[244:245], v[240:241], v[244:245], v[240:241]
	v_pk_mul_f32 v[242:243], v[178:179], v[242:243]
	v_pk_mul_f32 v[244:245], v[178:179], v[244:245]
	v_pk_add_f32 v[242:243], v[242:243], v[242:243]
	v_pk_add_f32 v[244:245], v[244:245], v[244:245]
	v_pk_mul_f32 v[242:243], v[180:181], v[242:243]
	v_pk_mul_f32 v[244:245], v[180:181], v[244:245]
	v_exp_f32_e32 v242, v242
	v_exp_f32_e32 v243, v243
	v_exp_f32_e32 v244, v244
	v_exp_f32_e32 v245, v245
	v_pk_add_f32 v[242:243], v[182:183], v[242:243]
	v_pk_add_f32 v[244:245], v[182:183], v[244:245]
	v_rcp_f32_e32 v242, v242
	v_rcp_f32_e32 v243, v243
	v_rcp_f32_e32 v244, v244
	v_rcp_f32_e32 v245, v245
	v_pk_mul_f32 v[238:239], v[238:239], v[242:243]
	v_pk_mul_f32 v[240:241], v[240:241], v[244:245]
	v_pk_mul_f32 v[96:97], v[96:97], v[238:239]
	v_pk_mul_f32 v[98:99], v[98:99], v[240:241]
	ds_read_u16 v214, v2 offset:16928
	ds_read_u16 v215, v2 offset:17456
	ds_read_u16 v216, v2 offset:17984
	ds_read_u16 v217, v2 offset:18512
	ds_read_u16 v218, v2 offset:19040
	ds_read_u16 v219, v2 offset:19568
	s_waitcnt lgkmcnt(6)
	v_lshlrev_b32_e32 v226, 16, v226
	v_lshlrev_b32_e32 v227, 16, v227
	v_lshlrev_b32_e32 v228, 16, v228
	v_lshlrev_b32_e32 v229, 16, v229
	v_lshlrev_b32_e32 v230, 16, v230
	v_lshlrev_b32_e32 v231, 16, v231
	v_mov_b32_e32 v232, v227
	v_mov_b32_e32 v233, v228
	v_mov_b32_e32 v234, v229
	v_mov_b32_e32 v235, v230
	v_mov_b32_e32 v236, v231
	v_pk_fma_f32 v[238:239], v[162:163], v[226:227], v[168:169]
	v_pk_fma_f32 v[240:241], v[162:163], v[228:229], v[168:169]
	v_pk_fma_f32 v[238:239], v[164:165], v[232:233], v[238:239]
	v_pk_fma_f32 v[240:241], v[164:165], v[234:235], v[240:241]
	v_pk_fma_f32 v[238:239], v[166:167], v[228:229], v[238:239]
	v_pk_fma_f32 v[240:241], v[166:167], v[230:231], v[240:241]
	v_pk_mul_f32 v[242:243], v[176:177], v[238:239]
	v_pk_mul_f32 v[244:245], v[176:177], v[240:241]
	v_pk_mul_f32 v[242:243], v[238:239], v[242:243]
	v_pk_mul_f32 v[244:245], v[240:241], v[244:245]
	v_pk_fma_f32 v[242:243], v[238:239], v[242:243], v[238:239]
	v_pk_fma_f32 v[244:245], v[240:241], v[244:245], v[240:241]
	v_pk_mul_f32 v[242:243], v[178:179], v[242:243]
	v_pk_mul_f32 v[244:245], v[178:179], v[244:245]
	v_pk_add_f32 v[242:243], v[242:243], v[242:243]
	v_pk_add_f32 v[244:245], v[244:245], v[244:245]
	v_pk_mul_f32 v[242:243], v[180:181], v[242:243]
	v_pk_mul_f32 v[244:245], v[180:181], v[244:245]
	v_exp_f32_e32 v242, v242
	v_exp_f32_e32 v243, v243
	v_exp_f32_e32 v244, v244
	v_exp_f32_e32 v245, v245
	v_pk_add_f32 v[242:243], v[182:183], v[242:243]
	v_pk_add_f32 v[244:245], v[182:183], v[244:245]
	v_rcp_f32_e32 v242, v242
	v_rcp_f32_e32 v243, v243
	v_rcp_f32_e32 v244, v244
	v_rcp_f32_e32 v245, v245
	v_pk_mul_f32 v[238:239], v[238:239], v[242:243]
	v_pk_mul_f32 v[240:241], v[240:241], v[244:245]
	v_pk_mul_f32 v[92:93], v[92:93], v[238:239]
	v_pk_mul_f32 v[94:95], v[94:95], v[240:241]
	ds_read_u16 v226, v2 offset:25376
	ds_read_u16 v227, v2 offset:25904
	ds_read_u16 v228, v2 offset:26432
	ds_read_u16 v229, v2 offset:26960
	ds_read_u16 v230, v2 offset:27488
	ds_read_u16 v231, v2 offset:28016
	s_waitcnt lgkmcnt(6)
; DI float bf2f(u16 h) { return __uint_as_float(((unsigned)h) << 16); }
; DI float gelu_tanh(float x) { float u = 0.7978845608028654f * (x + 0.044715f * x * x * x); return x * sigmoidf_(2.f * u); }
; DI void ffup_tile(const Params& p, int l, int mt, int nt, char* smem) {
;     ...
;     const u16* img = (const u16*)smem + (wr * 128 + fq * 4) * IMG_LD + wc * 64 + fr;
; #pragma unroll
;     for (int n = 0; n < 4; ++n) {
;       const int col = col0 + wc * 64 + n * 16 + fr;
;       const float* cw = p.in[30] + (size_t)l * 3 * DFF + col;
;       const float w0 = cw[0], w1 = cw[DFF], w2 = cw[2 * DFF], cb = p.in[31][(size_t)l * DFF + col];
; #pragma unroll
;       for (int m = 0; m < 8; ++m) {
;         if ((m & 1) == 0) asm volatile("" ::: "memory");
;         const int t = (row0 + wr * 128 + m * 16 + fq * 4) & 8191;
;         float g[6];
; #pragma unroll
;         for (int d = 0; d < 6; ++d) { const float gv = bf2f(img[(m * 16 + d) * IMG_LD + n * 16]); g[d] = (d >= 2 || t - 2 + d >= 0) ? gv : 0.f; }
; #pragma unroll
;         for (int j = 0; j < 4; ++j) acc[m][n][j] *= gelu_tanh(cb + w0 * g[j] + w1 * g[j + 1] + w2 * g[j + 2]);
;       }
	v_lshlrev_b32_e32 v214, 16, v214
	v_lshlrev_b32_e32 v215, 16, v215
	v_lshlrev_b32_e32 v216, 16, v216
	v_lshlrev_b32_e32 v217, 16, v217
	v_lshlrev_b32_e32 v218, 16, v218
	v_lshlrev_b32_e32 v219, 16, v219
	v_mov_b32_e32 v220, v215
	v_mov_b32_e32 v221, v216
	v_mov_b32_e32 v222, v217
	v_mov_b32_e32 v223, v218
	v_mov_b32_e32 v224, v219
	v_pk_fma_f32 v[238:239], v[162:163], v[214:215], v[168:169]
	v_pk_fma_f32 v[240:241], v[162:163], v[216:217], v[168:169]
	v_pk_fma_f32 v[238:239], v[164:165], v[220:221], v[238:239]
	v_pk_fma_f32 v[240:241], v[164:165], v[222:223], v[240:241]
	v_pk_fma_f32 v[238:239], v[166:167], v[216:217], v[238:239]
	v_pk_fma_f32 v[240:241], v[166:167], v[218:219], v[240:241]
	v_pk_mul_f32 v[242:243], v[176:177], v[238:239]
	v_pk_mul_f32 v[244:245], v[176:177], v[240:241]
	v_pk_mul_f32 v[242:243], v[238:239], v[242:243]
	v_pk_mul_f32 v[244:245], v[240:241], v[244:245]
	v_pk_fma_f32 v[242:243], v[238:239], v[242:243], v[238:239]
	v_pk_fma_f32 v[244:245], v[240:241], v[244:245], v[240:241]
	v_pk_mul_f32 v[242:243], v[178:179], v[242:243]
	v_pk_mul_f32 v[244:245], v[178:179], v[244:245]
	v_pk_add_f32 v[242:243], v[242:243], v[242:243]
	v_pk_add_f32 v[244:245], v[244:245], v[244:245]
	v_pk_mul_f32 v[242:243], v[180:181], v[242:243]
	v_pk_mul_f32 v[244:245], v[180:181], v[244:245]
	v_exp_f32_e32 v242, v242
	v_exp_f32_e32 v243, v243
	v_exp_f32_e32 v244, v244
	v_exp_f32_e32 v245, v245
	v_pk_add_f32 v[242:243], v[182:183], v[242:243]
	v_pk_add_f32 v[244:245], v[182:183], v[244:245]
	v_rcp_f32_e32 v242, v242
	v_rcp_f32_e32 v243, v243
	v_rcp_f32_e32 v244, v244
	v_rcp_f32_e32 v245, v245
	v_pk_mul_f32 v[238:239], v[238:239], v[242:243]
	v_pk_mul_f32 v[240:241], v[240:241], v[244:245]
	v_pk_mul_f32 v[88:89], v[88:89], v[238:239]
	v_pk_mul_f32 v[90:91], v[90:91], v[240:241]
	ds_read_u16 v214, v2 offset:33824
	ds_read_u16 v215, v2 offset:34352
	ds_read_u16 v216, v2 offset:34880
	ds_read_u16 v217, v2 offset:35408
	ds_read_u16 v218, v2 offset:35936
	ds_read_u16 v219, v2 offset:36464
	s_waitcnt lgkmcnt(6)
	v_lshlrev_b32_e32 v226, 16, v226
	v_lshlrev_b32_e32 v227, 16, v227
	v_lshlrev_b32_e32 v228, 16, v228
	v_lshlrev_b32_e32 v229, 16, v229
	v_lshlrev_b32_e32 v230, 16, v230
	v_lshlrev_b32_e32 v231, 16, v231
	v_mov_b32_e32 v232, v227
	v_mov_b32_e32 v233, v228
	v_mov_b32_e32 v234, v229
	v_mov_b32_e32 v235, v230
	v_mov_b32_e32 v236, v231
	v_pk_fma_f32 v[238:239], v[162:163], v[226:227], v[168:169]
	v_pk_fma_f32 v[240:241], v[162:163], v[228:229], v[168:169]
	v_pk_fma_f32 v[238:239], v[164:165], v[232:233], v[238:239]
	v_pk_fma_f32 v[240:241], v[164:165], v[234:235], v[240:241]
	v_pk_fma_f32 v[238:239], v[166:167], v[228:229], v[238:239]
	v_pk_fma_f32 v[240:241], v[166:167], v[230:231], v[240:241]
	v_pk_mul_f32 v[242:243], v[176:177], v[238:239]
	v_pk_mul_f32 v[244:245], v[176:177], v[240:241]
	v_pk_mul_f32 v[242:243], v[238:239], v[242:243]
	v_pk_mul_f32 v[244:245], v[240:241], v[244:245]
	v_pk_fma_f32 v[242:243], v[238:239], v[242:243], v[238:239]
	v_pk_fma_f32 v[244:245], v[240:241], v[244:245], v[240:241]
	v_pk_mul_f32 v[242:243], v[178:179], v[242:243]
	v_pk_mul_f32 v[244:245], v[178:179], v[244:245]
	v_pk_add_f32 v[242:243], v[242:243], v[242:243]
	v_pk_add_f32 v[244:245], v[244:245], v[244:245]
	v_pk_mul_f32 v[242:243], v[180:181], v[242:243]
	v_pk_mul_f32 v[244:245], v[180:181], v[244:245]
	v_exp_f32_e32 v242, v242
	v_exp_f32_e32 v243, v243
	v_exp_f32_e32 v244, v244
	v_exp_f32_e32 v245, v245
	v_pk_add_f32 v[242:243], v[182:183], v[242:243]
	v_pk_add_f32 v[244:245], v[182:183], v[244:245]
	v_rcp_f32_e32 v242, v242
	v_rcp_f32_e32 v243, v243
	v_rcp_f32_e32 v244, v244
	v_rcp_f32_e32 v245, v245
	v_pk_mul_f32 v[238:239], v[238:239], v[242:243]
	v_pk_mul_f32 v[240:241], v[240:241], v[244:245]
	v_pk_mul_f32 v[84:85], v[84:85], v[238:239]
	v_pk_mul_f32 v[86:87], v[86:87], v[240:241]
	ds_read_u16 v226, v2 offset:42272
	ds_read_u16 v227, v2 offset:42800
	ds_read_u16 v228, v2 offset:43328
	ds_read_u16 v229, v2 offset:43856
	ds_read_u16 v230, v2 offset:44384
	ds_read_u16 v231, v2 offset:44912
	s_waitcnt lgkmcnt(6)
	v_lshlrev_b32_e32 v214, 16, v214
	v_lshlrev_b32_e32 v215, 16, v215
	v_lshlrev_b32_e32 v216, 16, v216
	v_lshlrev_b32_e32 v217, 16, v217
	v_lshlrev_b32_e32 v218, 16, v218
	v_lshlrev_b32_e32 v219, 16, v219
	v_mov_b32_e32 v220, v215
	v_mov_b32_e32 v221, v216
	v_mov_b32_e32 v222, v217
	v_mov_b32_e32 v223, v218
	v_mov_b32_e32 v224, v219
	v_pk_fma_f32 v[238:239], v[162:163], v[214:215], v[168:169]
	v_pk_fma_f32 v[240:241], v[162:163], v[216:217], v[168:169]
	v_pk_fma_f32 v[238:239], v[164:165], v[220:221], v[238:239]
	v_pk_fma_f32 v[240:241], v[164:165], v[222:223], v[240:241]
	v_pk_fma_f32 v[238:239], v[166:167], v[216:217], v[238:239]
	v_pk_fma_f32 v[240:241], v[166:167], v[218:219], v[240:241]
	v_pk_mul_f32 v[242:243], v[176:177], v[238:239]
	v_pk_mul_f32 v[244:245], v[176:177], v[240:241]
	v_pk_mul_f32 v[242:243], v[238:239], v[242:243]
	v_pk_mul_f32 v[244:245], v[240:241], v[244:245]
	v_pk_fma_f32 v[242:243], v[238:239], v[242:243], v[238:239]
	v_pk_fma_f32 v[244:245], v[240:241], v[244:245], v[240:241]
	v_pk_mul_f32 v[242:243], v[178:179], v[242:243]
	v_pk_mul_f32 v[244:245], v[178:179], v[244:245]
	v_pk_add_f32 v[242:243], v[242:243], v[242:243]
	v_pk_add_f32 v[244:245], v[244:245], v[244:245]
	v_pk_mul_f32 v[242:243], v[180:181], v[242:243]
	v_pk_mul_f32 v[244:245], v[180:181], v[244:245]
	v_exp_f32_e32 v242, v242
	v_exp_f32_e32 v243, v243
	v_exp_f32_e32 v244, v244
	v_exp_f32_e32 v245, v245
	v_pk_add_f32 v[242:243], v[182:183], v[242:243]
	v_pk_add_f32 v[244:245], v[182:183], v[244:245]
	v_rcp_f32_e32 v242, v242
	v_rcp_f32_e32 v243, v243
	v_rcp_f32_e32 v244, v244
	v_rcp_f32_e32 v245, v245
	v_pk_mul_f32 v[238:239], v[238:239], v[242:243]
	v_pk_mul_f32 v[240:241], v[240:241], v[244:245]
	v_pk_mul_f32 v[80:81], v[80:81], v[238:239]
	v_pk_mul_f32 v[82:83], v[82:83], v[240:241]
	ds_read_u16 v214, v2 offset:50720
	ds_read_u16 v215, v2 offset:51248
	ds_read_u16 v216, v2 offset:51776
	ds_read_u16 v217, v2 offset:52304
	ds_read_u16 v218, v2 offset:52832
	ds_read_u16 v219, v2 offset:53360
	s_waitcnt lgkmcnt(6)
; DI float bf2f(u16 h) { return __uint_as_float(((unsigned)h) << 16); }
; DI float gelu_tanh(float x) { float u = 0.7978845608028654f * (x + 0.044715f * x * x * x); return x * sigmoidf_(2.f * u); }
; DI void ffup_tile(const Params& p, int l, int mt, int nt, char* smem) {
;     ...
; #pragma unroll
;     for (int n = 0; n < 4; ++n) {
;       const int col = col0 + wc * 64 + n * 16 + fr;
;       const float* cw = p.in[30] + (size_t)l * 3 * DFF + col;
;       const float w0 = cw[0], w1 = cw[DFF], w2 = cw[2 * DFF], cb = p.in[31][(size_t)l * DFF + col];
; #pragma unroll
;       for (int m = 0; m < 8; ++m) {
;         if ((m & 1) == 0) asm volatile("" ::: "memory");
;         const int t = (row0 + wr * 128 + m * 16 + fq * 4) & 8191;
;         float g[6];
; #pragma unroll
;         for (int d = 0; d < 6; ++d) { const float gv = bf2f(img[(m * 16 + d) * IMG_LD + n * 16]); g[d] = (d >= 2 || t - 2 + d >= 0) ? gv : 0.f; }
; #pragma unroll
;         for (int j = 0; j < 4; ++j) acc[m][n][j] *= gelu_tanh(cb + w0 * g[j] + w1 * g[j + 1] + w2 * g[j + 2]);
;       }
	v_lshlrev_b32_e32 v226, 16, v226
	v_lshlrev_b32_e32 v227, 16, v227
	v_lshlrev_b32_e32 v228, 16, v228
	v_lshlrev_b32_e32 v229, 16, v229
	v_lshlrev_b32_e32 v230, 16, v230
	v_lshlrev_b32_e32 v231, 16, v231
	v_mov_b32_e32 v232, v227
	v_mov_b32_e32 v233, v228
	v_mov_b32_e32 v234, v229
	v_mov_b32_e32 v235, v230
	v_mov_b32_e32 v236, v231
	v_pk_fma_f32 v[238:239], v[162:163], v[226:227], v[168:169]
	v_pk_fma_f32 v[240:241], v[162:163], v[228:229], v[168:169]
	v_pk_fma_f32 v[238:239], v[164:165], v[232:233], v[238:239]
	v_pk_fma_f32 v[240:241], v[164:165], v[234:235], v[240:241]
	v_pk_fma_f32 v[238:239], v[166:167], v[228:229], v[238:239]
	v_pk_fma_f32 v[240:241], v[166:167], v[230:231], v[240:241]
	v_pk_mul_f32 v[242:243], v[176:177], v[238:239]
	v_pk_mul_f32 v[244:245], v[176:177], v[240:241]
	v_pk_mul_f32 v[242:243], v[238:239], v[242:243]
	v_pk_mul_f32 v[244:245], v[240:241], v[244:245]
	v_pk_fma_f32 v[242:243], v[238:239], v[242:243], v[238:239]
	v_pk_fma_f32 v[244:245], v[240:241], v[244:245], v[240:241]
	v_pk_mul_f32 v[242:243], v[178:179], v[242:243]
	v_pk_mul_f32 v[244:245], v[178:179], v[244:245]
	v_pk_add_f32 v[242:243], v[242:243], v[242:243]
	v_pk_add_f32 v[244:245], v[244:245], v[244:245]
	v_pk_mul_f32 v[242:243], v[180:181], v[242:243]
	v_pk_mul_f32 v[244:245], v[180:181], v[244:245]
	v_exp_f32_e32 v242, v242
	v_exp_f32_e32 v243, v243
	v_exp_f32_e32 v244, v244
	v_exp_f32_e32 v245, v245
	v_pk_add_f32 v[242:243], v[182:183], v[242:243]
	v_pk_add_f32 v[244:245], v[182:183], v[244:245]
	v_rcp_f32_e32 v242, v242
	v_rcp_f32_e32 v243, v243
	v_rcp_f32_e32 v244, v244
	v_rcp_f32_e32 v245, v245
	v_pk_mul_f32 v[238:239], v[238:239], v[242:243]
	v_pk_mul_f32 v[240:241], v[240:241], v[244:245]
	v_pk_mul_f32 v[76:77], v[76:77], v[238:239]
	v_pk_mul_f32 v[78:79], v[78:79], v[240:241]
	ds_read_u16 v226, v2 offset:59168
	ds_read_u16 v227, v2 offset:59696
	ds_read_u16 v228, v2 offset:60224
	ds_read_u16 v229, v2 offset:60752
	ds_read_u16 v230, v2 offset:61280
	ds_read_u16 v231, v2 offset:61808
	s_waitcnt lgkmcnt(6)
	v_lshlrev_b32_e32 v214, 16, v214
	v_lshlrev_b32_e32 v215, 16, v215
	v_lshlrev_b32_e32 v216, 16, v216
	v_lshlrev_b32_e32 v217, 16, v217
	v_lshlrev_b32_e32 v218, 16, v218
	v_lshlrev_b32_e32 v219, 16, v219
	v_mov_b32_e32 v220, v215
	v_mov_b32_e32 v221, v216
	v_mov_b32_e32 v222, v217
	v_mov_b32_e32 v223, v218
	v_mov_b32_e32 v224, v219
	v_pk_fma_f32 v[238:239], v[162:163], v[214:215], v[168:169]
	v_pk_fma_f32 v[240:241], v[162:163], v[216:217], v[168:169]
	v_pk_fma_f32 v[238:239], v[164:165], v[220:221], v[238:239]
	v_pk_fma_f32 v[240:241], v[164:165], v[222:223], v[240:241]
	v_pk_fma_f32 v[238:239], v[166:167], v[216:217], v[238:239]
	v_pk_fma_f32 v[240:241], v[166:167], v[218:219], v[240:241]
	v_pk_mul_f32 v[242:243], v[176:177], v[238:239]
	v_pk_mul_f32 v[244:245], v[176:177], v[240:241]
	v_pk_mul_f32 v[242:243], v[238:239], v[242:243]
	v_pk_mul_f32 v[244:245], v[240:241], v[244:245]
	v_pk_fma_f32 v[242:243], v[238:239], v[242:243], v[238:239]
	v_pk_fma_f32 v[244:245], v[240:241], v[244:245], v[240:241]
	v_pk_mul_f32 v[242:243], v[178:179], v[242:243]
	v_pk_mul_f32 v[244:245], v[178:179], v[244:245]
	v_pk_add_f32 v[242:243], v[242:243], v[242:243]
	v_pk_add_f32 v[244:245], v[244:245], v[244:245]
	v_pk_mul_f32 v[242:243], v[180:181], v[242:243]
	v_pk_mul_f32 v[244:245], v[180:181], v[244:245]
	v_exp_f32_e32 v242, v242
	v_exp_f32_e32 v243, v243
	v_exp_f32_e32 v244, v244
	v_exp_f32_e32 v245, v245
	v_pk_add_f32 v[242:243], v[182:183], v[242:243]
	v_pk_add_f32 v[244:245], v[182:183], v[244:245]
	v_rcp_f32_e32 v242, v242
	v_rcp_f32_e32 v243, v243
	v_rcp_f32_e32 v244, v244
	v_rcp_f32_e32 v245, v245
	v_pk_mul_f32 v[238:239], v[238:239], v[242:243]
	v_pk_mul_f32 v[240:241], v[240:241], v[244:245]
	v_pk_mul_f32 v[72:73], v[72:73], v[238:239]
	v_pk_mul_f32 v[74:75], v[74:75], v[240:241]
	ds_read_u16 v214, v2 offset:64
	ds_read_u16 v215, v2 offset:592
	ds_read_u16 v216, v2 offset:1120
	ds_read_u16 v217, v2 offset:1648
	ds_read_u16 v218, v2 offset:2176
	ds_read_u16 v219, v2 offset:2704
	s_waitcnt lgkmcnt(6)
	v_lshlrev_b32_e32 v226, 16, v226
	v_lshlrev_b32_e32 v227, 16, v227
	v_lshlrev_b32_e32 v228, 16, v228
	v_lshlrev_b32_e32 v229, 16, v229
	v_lshlrev_b32_e32 v230, 16, v230
	v_lshlrev_b32_e32 v231, 16, v231
	v_mov_b32_e32 v232, v227
	v_mov_b32_e32 v233, v228
	v_mov_b32_e32 v234, v229
	v_mov_b32_e32 v235, v230
	v_mov_b32_e32 v236, v231
	v_pk_fma_f32 v[238:239], v[162:163], v[226:227], v[168:169]
	v_pk_fma_f32 v[240:241], v[162:163], v[228:229], v[168:169]
	v_pk_fma_f32 v[238:239], v[164:165], v[232:233], v[238:239]
	v_pk_fma_f32 v[240:241], v[164:165], v[234:235], v[240:241]
	v_pk_fma_f32 v[238:239], v[166:167], v[228:229], v[238:239]
	v_pk_fma_f32 v[240:241], v[166:167], v[230:231], v[240:241]
	v_pk_mul_f32 v[242:243], v[176:177], v[238:239]
	v_pk_mul_f32 v[244:245], v[176:177], v[240:241]
	v_pk_mul_f32 v[242:243], v[238:239], v[242:243]
	v_pk_mul_f32 v[244:245], v[240:241], v[244:245]
	v_pk_fma_f32 v[242:243], v[238:239], v[242:243], v[238:239]
	v_pk_fma_f32 v[244:245], v[240:241], v[244:245], v[240:241]
	v_pk_mul_f32 v[242:243], v[178:179], v[242:243]
	v_pk_mul_f32 v[244:245], v[178:179], v[244:245]
	v_pk_add_f32 v[242:243], v[242:243], v[242:243]
	v_pk_add_f32 v[244:245], v[244:245], v[244:245]
	v_pk_mul_f32 v[242:243], v[180:181], v[242:243]
	v_pk_mul_f32 v[244:245], v[180:181], v[244:245]
	v_exp_f32_e32 v242, v242
	v_exp_f32_e32 v243, v243
	v_exp_f32_e32 v244, v244
	v_exp_f32_e32 v245, v245
	v_pk_add_f32 v[242:243], v[182:183], v[242:243]
	v_pk_add_f32 v[244:245], v[182:183], v[244:245]
	v_rcp_f32_e32 v242, v242
	v_rcp_f32_e32 v243, v243
	v_rcp_f32_e32 v244, v244
	v_rcp_f32_e32 v245, v245
	v_pk_mul_f32 v[238:239], v[238:239], v[242:243]
	v_pk_mul_f32 v[240:241], v[240:241], v[244:245]
	v_pk_mul_f32 v[68:69], v[68:69], v[238:239]
	v_pk_mul_f32 v[70:71], v[70:71], v[240:241]
	ds_read_u16 v226, v2 offset:8512
	ds_read_u16 v227, v2 offset:9040
	ds_read_u16 v228, v2 offset:9568
	ds_read_u16 v229, v2 offset:10096
	ds_read_u16 v230, v2 offset:10624
	ds_read_u16 v231, v2 offset:11152
	s_waitcnt lgkmcnt(6)
; DI float bf2f(u16 h) { return __uint_as_float(((unsigned)h) << 16); }
; DI float gelu_tanh(float x) { float u = 0.7978845608028654f * (x + 0.044715f * x * x * x); return x * sigmoidf_(2.f * u); }
; DI void ffup_tile(const Params& p, int l, int mt, int nt, char* smem) {
;     ...
; #pragma unroll
;     for (int n = 0; n < 4; ++n) {
;       const int col = col0 + wc * 64 + n * 16 + fr;
;       const float* cw = p.in[30] + (size_t)l * 3 * DFF + col;
;       const float w0 = cw[0], w1 = cw[DFF], w2 = cw[2 * DFF], cb = p.in[31][(size_t)l * DFF + col];
; #pragma unroll
;       for (int m = 0; m < 8; ++m) {
;         if ((m & 1) == 0) asm volatile("" ::: "memory");
;         const int t = (row0 + wr * 128 + m * 16 + fq * 4) & 8191;
;         float g[6];
; #pragma unroll
;         for (int d = 0; d < 6; ++d) { const float gv = bf2f(img[(m * 16 + d) * IMG_LD + n * 16]); g[d] = (d >= 2 || t - 2 + d >= 0) ? gv : 0.f; }
; #pragma unroll
;         for (int j = 0; j < 4; ++j) acc[m][n][j] *= gelu_tanh(cb + w0 * g[j] + w1 * g[j + 1] + w2 * g[j + 2]);
;       }
	s_waitcnt vmcnt(4)
	v_mov_b32_e32 v162, v154
	v_mov_b32_e32 v163, v154
	v_mov_b32_e32 v164, v155
	v_mov_b32_e32 v165, v155
	v_mov_b32_e32 v166, v156
	v_mov_b32_e32 v167, v156
	v_mov_b32_e32 v168, v157
	v_mov_b32_e32 v169, v157
	v_lshlrev_b32_e32 v214, 16, v214
	v_lshlrev_b32_e32 v215, 16, v215
	v_lshlrev_b32_e32 v216, 16, v216
	v_lshlrev_b32_e32 v217, 16, v217
	v_lshlrev_b32_e32 v218, 16, v218
	v_lshlrev_b32_e32 v219, 16, v219
	v_cndmask_b32_e64 v214, v214, 0, vcc
	v_cndmask_b32_e64 v215, v215, 0, vcc
	v_mov_b32_e32 v220, v215
	v_mov_b32_e32 v221, v216
	v_mov_b32_e32 v222, v217
	v_mov_b32_e32 v223, v218
	v_mov_b32_e32 v224, v219
	v_pk_fma_f32 v[238:239], v[162:163], v[214:215], v[168:169]
	v_pk_fma_f32 v[240:241], v[162:163], v[216:217], v[168:169]
	v_pk_fma_f32 v[238:239], v[164:165], v[220:221], v[238:239]
	v_pk_fma_f32 v[240:241], v[164:165], v[222:223], v[240:241]
	v_pk_fma_f32 v[238:239], v[166:167], v[216:217], v[238:239]
	v_pk_fma_f32 v[240:241], v[166:167], v[218:219], v[240:241]
	v_pk_mul_f32 v[242:243], v[176:177], v[238:239]
	v_pk_mul_f32 v[244:245], v[176:177], v[240:241]
	v_pk_mul_f32 v[242:243], v[238:239], v[242:243]
	v_pk_mul_f32 v[244:245], v[240:241], v[244:245]
	v_pk_fma_f32 v[242:243], v[238:239], v[242:243], v[238:239]
	v_pk_fma_f32 v[244:245], v[240:241], v[244:245], v[240:241]
	v_pk_mul_f32 v[242:243], v[178:179], v[242:243]
	v_pk_mul_f32 v[244:245], v[178:179], v[244:245]
	v_pk_add_f32 v[242:243], v[242:243], v[242:243]
	v_pk_add_f32 v[244:245], v[244:245], v[244:245]
	v_pk_mul_f32 v[242:243], v[180:181], v[242:243]
	v_pk_mul_f32 v[244:245], v[180:181], v[244:245]
	v_exp_f32_e32 v242, v242
	v_exp_f32_e32 v243, v243
	v_exp_f32_e32 v244, v244
	v_exp_f32_e32 v245, v245
	v_pk_add_f32 v[242:243], v[182:183], v[242:243]
	v_pk_add_f32 v[244:245], v[182:183], v[244:245]
	v_rcp_f32_e32 v242, v242
	v_rcp_f32_e32 v243, v243
	v_rcp_f32_e32 v244, v244
	v_rcp_f32_e32 v245, v245
	v_pk_mul_f32 v[238:239], v[238:239], v[242:243]
	v_pk_mul_f32 v[240:241], v[240:241], v[244:245]
	v_pk_mul_f32 v[64:65], v[64:65], v[238:239]
	v_pk_mul_f32 v[66:67], v[66:67], v[240:241]
	ds_read_u16 v214, v2 offset:16960
	ds_read_u16 v215, v2 offset:17488
	ds_read_u16 v216, v2 offset:18016
	ds_read_u16 v217, v2 offset:18544
	ds_read_u16 v218, v2 offset:19072
	ds_read_u16 v219, v2 offset:19600
	s_waitcnt lgkmcnt(6)
	v_lshlrev_b32_e32 v226, 16, v226
	v_lshlrev_b32_e32 v227, 16, v227
	v_lshlrev_b32_e32 v228, 16, v228
	v_lshlrev_b32_e32 v229, 16, v229
	v_lshlrev_b32_e32 v230, 16, v230
	v_lshlrev_b32_e32 v231, 16, v231
	v_mov_b32_e32 v232, v227
	v_mov_b32_e32 v233, v228
	v_mov_b32_e32 v234, v229
	v_mov_b32_e32 v235, v230
	v_mov_b32_e32 v236, v231
	v_pk_fma_f32 v[238:239], v[162:163], v[226:227], v[168:169]
	v_pk_fma_f32 v[240:241], v[162:163], v[228:229], v[168:169]
	v_pk_fma_f32 v[238:239], v[164:165], v[232:233], v[238:239]
	v_pk_fma_f32 v[240:241], v[164:165], v[234:235], v[240:241]
	v_pk_fma_f32 v[238:239], v[166:167], v[228:229], v[238:239]
	v_pk_fma_f32 v[240:241], v[166:167], v[230:231], v[240:241]
	v_pk_mul_f32 v[242:243], v[176:177], v[238:239]
	v_pk_mul_f32 v[244:245], v[176:177], v[240:241]
	v_pk_mul_f32 v[242:243], v[238:239], v[242:243]
	v_pk_mul_f32 v[244:245], v[240:241], v[244:245]
	v_pk_fma_f32 v[242:243], v[238:239], v[242:243], v[238:239]
	v_pk_fma_f32 v[244:245], v[240:241], v[244:245], v[240:241]
	v_pk_mul_f32 v[242:243], v[178:179], v[242:243]
	v_pk_mul_f32 v[244:245], v[178:179], v[244:245]
	v_pk_add_f32 v[242:243], v[242:243], v[242:243]
	v_pk_add_f32 v[244:245], v[244:245], v[244:245]
	v_pk_mul_f32 v[242:243], v[180:181], v[242:243]
	v_pk_mul_f32 v[244:245], v[180:181], v[244:245]
	v_exp_f32_e32 v242, v242
	v_exp_f32_e32 v243, v243
	v_exp_f32_e32 v244, v244
	v_exp_f32_e32 v245, v245
	v_pk_add_f32 v[242:243], v[182:183], v[242:243]
	v_pk_add_f32 v[244:245], v[182:183], v[244:245]
	v_rcp_f32_e32 v242, v242
	v_rcp_f32_e32 v243, v243
	v_rcp_f32_e32 v244, v244
	v_rcp_f32_e32 v245, v245
	v_pk_mul_f32 v[238:239], v[238:239], v[242:243]
	v_pk_mul_f32 v[240:241], v[240:241], v[244:245]
	v_pk_mul_f32 v[60:61], v[60:61], v[238:239]
	v_pk_mul_f32 v[62:63], v[62:63], v[240:241]
	ds_read_u16 v226, v2 offset:25408
	ds_read_u16 v227, v2 offset:25936
	ds_read_u16 v228, v2 offset:26464
	ds_read_u16 v229, v2 offset:26992
	ds_read_u16 v230, v2 offset:27520
	ds_read_u16 v231, v2 offset:28048
	s_waitcnt lgkmcnt(6)
	v_lshlrev_b32_e32 v214, 16, v214
	v_lshlrev_b32_e32 v215, 16, v215
	v_lshlrev_b32_e32 v216, 16, v216
	v_lshlrev_b32_e32 v217, 16, v217
	v_lshlrev_b32_e32 v218, 16, v218
	v_lshlrev_b32_e32 v219, 16, v219
	v_mov_b32_e32 v220, v215
	v_mov_b32_e32 v221, v216
	v_mov_b32_e32 v222, v217
	v_mov_b32_e32 v223, v218
	v_mov_b32_e32 v224, v219
	v_pk_fma_f32 v[238:239], v[162:163], v[214:215], v[168:169]
	v_pk_fma_f32 v[240:241], v[162:163], v[216:217], v[168:169]
	v_pk_fma_f32 v[238:239], v[164:165], v[220:221], v[238:239]
	v_pk_fma_f32 v[240:241], v[164:165], v[222:223], v[240:241]
	v_pk_fma_f32 v[238:239], v[166:167], v[216:217], v[238:239]
	v_pk_fma_f32 v[240:241], v[166:167], v[218:219], v[240:241]
	v_pk_mul_f32 v[242:243], v[176:177], v[238:239]
	v_pk_mul_f32 v[244:245], v[176:177], v[240:241]
	v_pk_mul_f32 v[242:243], v[238:239], v[242:243]
	v_pk_mul_f32 v[244:245], v[240:241], v[244:245]
	v_pk_fma_f32 v[242:243], v[238:239], v[242:243], v[238:239]
	v_pk_fma_f32 v[244:245], v[240:241], v[244:245], v[240:241]
	v_pk_mul_f32 v[242:243], v[178:179], v[242:243]
	v_pk_mul_f32 v[244:245], v[178:179], v[244:245]
	v_pk_add_f32 v[242:243], v[242:243], v[242:243]
	v_pk_add_f32 v[244:245], v[244:245], v[244:245]
	v_pk_mul_f32 v[242:243], v[180:181], v[242:243]
	v_pk_mul_f32 v[244:245], v[180:181], v[244:245]
	v_exp_f32_e32 v242, v242
	v_exp_f32_e32 v243, v243
	v_exp_f32_e32 v244, v244
	v_exp_f32_e32 v245, v245
	v_pk_add_f32 v[242:243], v[182:183], v[242:243]
	v_pk_add_f32 v[244:245], v[182:183], v[244:245]
	v_rcp_f32_e32 v242, v242
	v_rcp_f32_e32 v243, v243
	v_rcp_f32_e32 v244, v244
	v_rcp_f32_e32 v245, v245
	v_pk_mul_f32 v[238:239], v[238:239], v[242:243]
	v_pk_mul_f32 v[240:241], v[240:241], v[244:245]
	v_pk_mul_f32 v[56:57], v[56:57], v[238:239]
	v_pk_mul_f32 v[58:59], v[58:59], v[240:241]
	ds_read_u16 v214, v2 offset:33856
	ds_read_u16 v215, v2 offset:34384
	ds_read_u16 v216, v2 offset:34912
	ds_read_u16 v217, v2 offset:35440
	ds_read_u16 v218, v2 offset:35968
	ds_read_u16 v219, v2 offset:36496
	s_waitcnt lgkmcnt(6)
; DI float bf2f(u16 h) { return __uint_as_float(((unsigned)h) << 16); }
; DI float gelu_tanh(float x) { float u = 0.7978845608028654f * (x + 0.044715f * x * x * x); return x * sigmoidf_(2.f * u); }
; DI void ffup_tile(const Params& p, int l, int mt, int nt, char* smem) {
;     ...
; #pragma unroll
;     for (int n = 0; n < 4; ++n) {
;       const int col = col0 + wc * 64 + n * 16 + fr;
;       const float* cw = p.in[30] + (size_t)l * 3 * DFF + col;
;       const float w0 = cw[0], w1 = cw[DFF], w2 = cw[2 * DFF], cb = p.in[31][(size_t)l * DFF + col];
; #pragma unroll
;       for (int m = 0; m < 8; ++m) {
;         if ((m & 1) == 0) asm volatile("" ::: "memory");
;         const int t = (row0 + wr * 128 + m * 16 + fq * 4) & 8191;
;         float g[6];
; #pragma unroll
;         for (int d = 0; d < 6; ++d) { const float gv = bf2f(img[(m * 16 + d) * IMG_LD + n * 16]); g[d] = (d >= 2 || t - 2 + d >= 0) ? gv : 0.f; }
; #pragma unroll
;         for (int j = 0; j < 4; ++j) acc[m][n][j] *= gelu_tanh(cb + w0 * g[j] + w1 * g[j + 1] + w2 * g[j + 2]);
;       }
	v_lshlrev_b32_e32 v226, 16, v226
	v_lshlrev_b32_e32 v227, 16, v227
	v_lshlrev_b32_e32 v228, 16, v228
	v_lshlrev_b32_e32 v229, 16, v229
	v_lshlrev_b32_e32 v230, 16, v230
	v_lshlrev_b32_e32 v231, 16, v231
	v_mov_b32_e32 v232, v227
	v_mov_b32_e32 v233, v228
	v_mov_b32_e32 v234, v229
	v_mov_b32_e32 v235, v230
	v_mov_b32_e32 v236, v231
	v_pk_fma_f32 v[238:239], v[162:163], v[226:227], v[168:169]
	v_pk_fma_f32 v[240:241], v[162:163], v[228:229], v[168:169]
	v_pk_fma_f32 v[238:239], v[164:165], v[232:233], v[238:239]
	v_pk_fma_f32 v[240:241], v[164:165], v[234:235], v[240:241]
	v_pk_fma_f32 v[238:239], v[166:167], v[228:229], v[238:239]
	v_pk_fma_f32 v[240:241], v[166:167], v[230:231], v[240:241]
	v_pk_mul_f32 v[242:243], v[176:177], v[238:239]
	v_pk_mul_f32 v[244:245], v[176:177], v[240:241]
	v_pk_mul_f32 v[242:243], v[238:239], v[242:243]
	v_pk_mul_f32 v[244:245], v[240:241], v[244:245]
	v_pk_fma_f32 v[242:243], v[238:239], v[242:243], v[238:239]
	v_pk_fma_f32 v[244:245], v[240:241], v[244:245], v[240:241]
	v_pk_mul_f32 v[242:243], v[178:179], v[242:243]
	v_pk_mul_f32 v[244:245], v[178:179], v[244:245]
	v_pk_add_f32 v[242:243], v[242:243], v[242:243]
	v_pk_add_f32 v[244:245], v[244:245], v[244:245]
	v_pk_mul_f32 v[242:243], v[180:181], v[242:243]
	v_pk_mul_f32 v[244:245], v[180:181], v[244:245]
	v_exp_f32_e32 v242, v242
	v_exp_f32_e32 v243, v243
	v_exp_f32_e32 v244, v244
	v_exp_f32_e32 v245, v245
	v_pk_add_f32 v[242:243], v[182:183], v[242:243]
	v_pk_add_f32 v[244:245], v[182:183], v[244:245]
	v_rcp_f32_e32 v242, v242
	v_rcp_f32_e32 v243, v243
	v_rcp_f32_e32 v244, v244
	v_rcp_f32_e32 v245, v245
	v_pk_mul_f32 v[238:239], v[238:239], v[242:243]
	v_pk_mul_f32 v[240:241], v[240:241], v[244:245]
	v_pk_mul_f32 v[52:53], v[52:53], v[238:239]
	v_pk_mul_f32 v[54:55], v[54:55], v[240:241]
	ds_read_u16 v226, v2 offset:42304
	ds_read_u16 v227, v2 offset:42832
	ds_read_u16 v228, v2 offset:43360
	ds_read_u16 v229, v2 offset:43888
	ds_read_u16 v230, v2 offset:44416
	ds_read_u16 v231, v2 offset:44944
	s_waitcnt lgkmcnt(6)
	v_lshlrev_b32_e32 v214, 16, v214
	v_lshlrev_b32_e32 v215, 16, v215
	v_lshlrev_b32_e32 v216, 16, v216
	v_lshlrev_b32_e32 v217, 16, v217
	v_lshlrev_b32_e32 v218, 16, v218
	v_lshlrev_b32_e32 v219, 16, v219
	v_mov_b32_e32 v220, v215
	v_mov_b32_e32 v221, v216
	v_mov_b32_e32 v222, v217
	v_mov_b32_e32 v223, v218
	v_mov_b32_e32 v224, v219
	v_pk_fma_f32 v[238:239], v[162:163], v[214:215], v[168:169]
	v_pk_fma_f32 v[240:241], v[162:163], v[216:217], v[168:169]
	v_pk_fma_f32 v[238:239], v[164:165], v[220:221], v[238:239]
	v_pk_fma_f32 v[240:241], v[164:165], v[222:223], v[240:241]
	v_pk_fma_f32 v[238:239], v[166:167], v[216:217], v[238:239]
	v_pk_fma_f32 v[240:241], v[166:167], v[218:219], v[240:241]
	v_pk_mul_f32 v[242:243], v[176:177], v[238:239]
	v_pk_mul_f32 v[244:245], v[176:177], v[240:241]
	v_pk_mul_f32 v[242:243], v[238:239], v[242:243]
	v_pk_mul_f32 v[244:245], v[240:241], v[244:245]
	v_pk_fma_f32 v[242:243], v[238:239], v[242:243], v[238:239]
	v_pk_fma_f32 v[244:245], v[240:241], v[244:245], v[240:241]
	v_pk_mul_f32 v[242:243], v[178:179], v[242:243]
	v_pk_mul_f32 v[244:245], v[178:179], v[244:245]
	v_pk_add_f32 v[242:243], v[242:243], v[242:243]
	v_pk_add_f32 v[244:245], v[244:245], v[244:245]
	v_pk_mul_f32 v[242:243], v[180:181], v[242:243]
	v_pk_mul_f32 v[244:245], v[180:181], v[244:245]
	v_exp_f32_e32 v242, v242
	v_exp_f32_e32 v243, v243
	v_exp_f32_e32 v244, v244
	v_exp_f32_e32 v245, v245
	v_pk_add_f32 v[242:243], v[182:183], v[242:243]
	v_pk_add_f32 v[244:245], v[182:183], v[244:245]
	v_rcp_f32_e32 v242, v242
	v_rcp_f32_e32 v243, v243
	v_rcp_f32_e32 v244, v244
	v_rcp_f32_e32 v245, v245
	v_pk_mul_f32 v[238:239], v[238:239], v[242:243]
	v_pk_mul_f32 v[240:241], v[240:241], v[244:245]
	v_pk_mul_f32 v[48:49], v[48:49], v[238:239]
	v_pk_mul_f32 v[50:51], v[50:51], v[240:241]
	ds_read_u16 v214, v2 offset:50752
	ds_read_u16 v215, v2 offset:51280
	ds_read_u16 v216, v2 offset:51808
	ds_read_u16 v217, v2 offset:52336
	ds_read_u16 v218, v2 offset:52864
	ds_read_u16 v219, v2 offset:53392
	s_waitcnt lgkmcnt(6)
	v_lshlrev_b32_e32 v226, 16, v226
	v_lshlrev_b32_e32 v227, 16, v227
	v_lshlrev_b32_e32 v228, 16, v228
	v_lshlrev_b32_e32 v229, 16, v229
	v_lshlrev_b32_e32 v230, 16, v230
	v_lshlrev_b32_e32 v231, 16, v231
	v_mov_b32_e32 v232, v227
	v_mov_b32_e32 v233, v228
	v_mov_b32_e32 v234, v229
	v_mov_b32_e32 v235, v230
	v_mov_b32_e32 v236, v231
	v_pk_fma_f32 v[238:239], v[162:163], v[226:227], v[168:169]
	v_pk_fma_f32 v[240:241], v[162:163], v[228:229], v[168:169]
	v_pk_fma_f32 v[238:239], v[164:165], v[232:233], v[238:239]
	v_pk_fma_f32 v[240:241], v[164:165], v[234:235], v[240:241]
	v_pk_fma_f32 v[238:239], v[166:167], v[228:229], v[238:239]
	v_pk_fma_f32 v[240:241], v[166:167], v[230:231], v[240:241]
	v_pk_mul_f32 v[242:243], v[176:177], v[238:239]
	v_pk_mul_f32 v[244:245], v[176:177], v[240:241]
	v_pk_mul_f32 v[242:243], v[238:239], v[242:243]
	v_pk_mul_f32 v[244:245], v[240:241], v[244:245]
	v_pk_fma_f32 v[242:243], v[238:239], v[242:243], v[238:239]
	v_pk_fma_f32 v[244:245], v[240:241], v[244:245], v[240:241]
	v_pk_mul_f32 v[242:243], v[178:179], v[242:243]
	v_pk_mul_f32 v[244:245], v[178:179], v[244:245]
	v_pk_add_f32 v[242:243], v[242:243], v[242:243]
	v_pk_add_f32 v[244:245], v[244:245], v[244:245]
	v_pk_mul_f32 v[242:243], v[180:181], v[242:243]
	v_pk_mul_f32 v[244:245], v[180:181], v[244:245]
	v_exp_f32_e32 v242, v242
	v_exp_f32_e32 v243, v243
	v_exp_f32_e32 v244, v244
	v_exp_f32_e32 v245, v245
	v_pk_add_f32 v[242:243], v[182:183], v[242:243]
	v_pk_add_f32 v[244:245], v[182:183], v[244:245]
	v_rcp_f32_e32 v242, v242
	v_rcp_f32_e32 v243, v243
	v_rcp_f32_e32 v244, v244
	v_rcp_f32_e32 v245, v245
	v_pk_mul_f32 v[238:239], v[238:239], v[242:243]
	v_pk_mul_f32 v[240:241], v[240:241], v[244:245]
	v_pk_mul_f32 v[44:45], v[44:45], v[238:239]
	v_pk_mul_f32 v[46:47], v[46:47], v[240:241]
	ds_read_u16 v226, v2 offset:59200
	ds_read_u16 v227, v2 offset:59728
	ds_read_u16 v228, v2 offset:60256
	ds_read_u16 v229, v2 offset:60784
	ds_read_u16 v230, v2 offset:61312
	ds_read_u16 v231, v2 offset:61840
	s_waitcnt lgkmcnt(6)
; DI float bf2f(u16 h) { return __uint_as_float(((unsigned)h) << 16); }
; DI float gelu_tanh(float x) { float u = 0.7978845608028654f * (x + 0.044715f * x * x * x); return x * sigmoidf_(2.f * u); }
; DI void ffup_tile(const Params& p, int l, int mt, int nt, char* smem) {
;     ...
; #pragma unroll
;     for (int n = 0; n < 4; ++n) {
;       const int col = col0 + wc * 64 + n * 16 + fr;
;       const float* cw = p.in[30] + (size_t)l * 3 * DFF + col;
;       const float w0 = cw[0], w1 = cw[DFF], w2 = cw[2 * DFF], cb = p.in[31][(size_t)l * DFF + col];
; #pragma unroll
;       for (int m = 0; m < 8; ++m) {
;         if ((m & 1) == 0) asm volatile("" ::: "memory");
;         const int t = (row0 + wr * 128 + m * 16 + fq * 4) & 8191;
;         float g[6];
; #pragma unroll
;         for (int d = 0; d < 6; ++d) { const float gv = bf2f(img[(m * 16 + d) * IMG_LD + n * 16]); g[d] = (d >= 2 || t - 2 + d >= 0) ? gv : 0.f; }
; #pragma unroll
;         for (int j = 0; j < 4; ++j) acc[m][n][j] *= gelu_tanh(cb + w0 * g[j] + w1 * g[j + 1] + w2 * g[j + 2]);
;       }
	v_lshlrev_b32_e32 v214, 16, v214
	v_lshlrev_b32_e32 v215, 16, v215
	v_lshlrev_b32_e32 v216, 16, v216
	v_lshlrev_b32_e32 v217, 16, v217
	v_lshlrev_b32_e32 v218, 16, v218
	v_lshlrev_b32_e32 v219, 16, v219
	v_mov_b32_e32 v220, v215
	v_mov_b32_e32 v221, v216
	v_mov_b32_e32 v222, v217
	v_mov_b32_e32 v223, v218
	v_mov_b32_e32 v224, v219
	v_pk_fma_f32 v[238:239], v[162:163], v[214:215], v[168:169]
	v_pk_fma_f32 v[240:241], v[162:163], v[216:217], v[168:169]
	v_pk_fma_f32 v[238:239], v[164:165], v[220:221], v[238:239]
	v_pk_fma_f32 v[240:241], v[164:165], v[222:223], v[240:241]
	v_pk_fma_f32 v[238:239], v[166:167], v[216:217], v[238:239]
	v_pk_fma_f32 v[240:241], v[166:167], v[218:219], v[240:241]
	v_pk_mul_f32 v[242:243], v[176:177], v[238:239]
	v_pk_mul_f32 v[244:245], v[176:177], v[240:241]
	v_pk_mul_f32 v[242:243], v[238:239], v[242:243]
	v_pk_mul_f32 v[244:245], v[240:241], v[244:245]
	v_pk_fma_f32 v[242:243], v[238:239], v[242:243], v[238:239]
	v_pk_fma_f32 v[244:245], v[240:241], v[244:245], v[240:241]
	v_pk_mul_f32 v[242:243], v[178:179], v[242:243]
	v_pk_mul_f32 v[244:245], v[178:179], v[244:245]
	v_pk_add_f32 v[242:243], v[242:243], v[242:243]
	v_pk_add_f32 v[244:245], v[244:245], v[244:245]
	v_pk_mul_f32 v[242:243], v[180:181], v[242:243]
	v_pk_mul_f32 v[244:245], v[180:181], v[244:245]
	v_exp_f32_e32 v242, v242
	v_exp_f32_e32 v243, v243
	v_exp_f32_e32 v244, v244
	v_exp_f32_e32 v245, v245
	v_pk_add_f32 v[242:243], v[182:183], v[242:243]
	v_pk_add_f32 v[244:245], v[182:183], v[244:245]
	v_rcp_f32_e32 v242, v242
	v_rcp_f32_e32 v243, v243
	v_rcp_f32_e32 v244, v244
	v_rcp_f32_e32 v245, v245
	v_pk_mul_f32 v[238:239], v[238:239], v[242:243]
	v_pk_mul_f32 v[240:241], v[240:241], v[244:245]
	v_pk_mul_f32 v[40:41], v[40:41], v[238:239]
	v_pk_mul_f32 v[42:43], v[42:43], v[240:241]
	ds_read_u16 v214, v2 offset:96
	ds_read_u16 v215, v2 offset:624
	ds_read_u16 v216, v2 offset:1152
	ds_read_u16 v217, v2 offset:1680
	ds_read_u16 v218, v2 offset:2208
	ds_read_u16 v219, v2 offset:2736
	s_waitcnt lgkmcnt(6)
	v_lshlrev_b32_e32 v226, 16, v226
	v_lshlrev_b32_e32 v227, 16, v227
	v_lshlrev_b32_e32 v228, 16, v228
	v_lshlrev_b32_e32 v229, 16, v229
	v_lshlrev_b32_e32 v230, 16, v230
	v_lshlrev_b32_e32 v231, 16, v231
	v_mov_b32_e32 v232, v227
	v_mov_b32_e32 v233, v228
	v_mov_b32_e32 v234, v229
	v_mov_b32_e32 v235, v230
	v_mov_b32_e32 v236, v231
	v_pk_fma_f32 v[238:239], v[162:163], v[226:227], v[168:169]
	v_pk_fma_f32 v[240:241], v[162:163], v[228:229], v[168:169]
	v_pk_fma_f32 v[238:239], v[164:165], v[232:233], v[238:239]
	v_pk_fma_f32 v[240:241], v[164:165], v[234:235], v[240:241]
	v_pk_fma_f32 v[238:239], v[166:167], v[228:229], v[238:239]
	v_pk_fma_f32 v[240:241], v[166:167], v[230:231], v[240:241]
	v_pk_mul_f32 v[242:243], v[176:177], v[238:239]
	v_pk_mul_f32 v[244:245], v[176:177], v[240:241]
	v_pk_mul_f32 v[242:243], v[238:239], v[242:243]
	v_pk_mul_f32 v[244:245], v[240:241], v[244:245]
	v_pk_fma_f32 v[242:243], v[238:239], v[242:243], v[238:239]
	v_pk_fma_f32 v[244:245], v[240:241], v[244:245], v[240:241]
	v_pk_mul_f32 v[242:243], v[178:179], v[242:243]
	v_pk_mul_f32 v[244:245], v[178:179], v[244:245]
	v_pk_add_f32 v[242:243], v[242:243], v[242:243]
	v_pk_add_f32 v[244:245], v[244:245], v[244:245]
	v_pk_mul_f32 v[242:243], v[180:181], v[242:243]
	v_pk_mul_f32 v[244:245], v[180:181], v[244:245]
	v_exp_f32_e32 v242, v242
	v_exp_f32_e32 v243, v243
	v_exp_f32_e32 v244, v244
	v_exp_f32_e32 v245, v245
	v_pk_add_f32 v[242:243], v[182:183], v[242:243]
	v_pk_add_f32 v[244:245], v[182:183], v[244:245]
	v_rcp_f32_e32 v242, v242
	v_rcp_f32_e32 v243, v243
	v_rcp_f32_e32 v244, v244
	v_rcp_f32_e32 v245, v245
	v_pk_mul_f32 v[238:239], v[238:239], v[242:243]
	v_pk_mul_f32 v[240:241], v[240:241], v[244:245]
	v_pk_mul_f32 v[36:37], v[36:37], v[238:239]
	v_pk_mul_f32 v[38:39], v[38:39], v[240:241]
	ds_read_u16 v226, v2 offset:8544
	ds_read_u16 v227, v2 offset:9072
	ds_read_u16 v228, v2 offset:9600
	ds_read_u16 v229, v2 offset:10128
	ds_read_u16 v230, v2 offset:10656
	ds_read_u16 v231, v2 offset:11184
	s_waitcnt lgkmcnt(6)
	s_waitcnt vmcnt(0)
	v_mov_b32_e32 v162, v158
	v_mov_b32_e32 v163, v158
	v_mov_b32_e32 v164, v159
	v_mov_b32_e32 v165, v159
	v_mov_b32_e32 v166, v160
	v_mov_b32_e32 v167, v160
	v_mov_b32_e32 v168, v161
	v_mov_b32_e32 v169, v161
	v_lshlrev_b32_e32 v214, 16, v214
	v_lshlrev_b32_e32 v215, 16, v215
	v_lshlrev_b32_e32 v216, 16, v216
	v_lshlrev_b32_e32 v217, 16, v217
	v_lshlrev_b32_e32 v218, 16, v218
	v_lshlrev_b32_e32 v219, 16, v219
	v_cndmask_b32_e64 v214, v214, 0, vcc
	v_cndmask_b32_e64 v215, v215, 0, vcc
	v_mov_b32_e32 v220, v215
	v_mov_b32_e32 v221, v216
	v_mov_b32_e32 v222, v217
	v_mov_b32_e32 v223, v218
	v_mov_b32_e32 v224, v219
	v_pk_fma_f32 v[238:239], v[162:163], v[214:215], v[168:169]
	v_pk_fma_f32 v[240:241], v[162:163], v[216:217], v[168:169]
	v_pk_fma_f32 v[238:239], v[164:165], v[220:221], v[238:239]
	v_pk_fma_f32 v[240:241], v[164:165], v[222:223], v[240:241]
	v_pk_fma_f32 v[238:239], v[166:167], v[216:217], v[238:239]
	v_pk_fma_f32 v[240:241], v[166:167], v[218:219], v[240:241]
	v_pk_mul_f32 v[242:243], v[176:177], v[238:239]
	v_pk_mul_f32 v[244:245], v[176:177], v[240:241]
	v_pk_mul_f32 v[242:243], v[238:239], v[242:243]
	v_pk_mul_f32 v[244:245], v[240:241], v[244:245]
	v_pk_fma_f32 v[242:243], v[238:239], v[242:243], v[238:239]
	v_pk_fma_f32 v[244:245], v[240:241], v[244:245], v[240:241]
	v_pk_mul_f32 v[242:243], v[178:179], v[242:243]
	v_pk_mul_f32 v[244:245], v[178:179], v[244:245]
	v_pk_add_f32 v[242:243], v[242:243], v[242:243]
	v_pk_add_f32 v[244:245], v[244:245], v[244:245]
	v_pk_mul_f32 v[242:243], v[180:181], v[242:243]
	v_pk_mul_f32 v[244:245], v[180:181], v[244:245]
	v_exp_f32_e32 v242, v242
	v_exp_f32_e32 v243, v243
	v_exp_f32_e32 v244, v244
	v_exp_f32_e32 v245, v245
	v_pk_add_f32 v[242:243], v[182:183], v[242:243]
	v_pk_add_f32 v[244:245], v[182:183], v[244:245]
	v_rcp_f32_e32 v242, v242
	v_rcp_f32_e32 v243, v243
	v_rcp_f32_e32 v244, v244
	v_rcp_f32_e32 v245, v245
	v_pk_mul_f32 v[238:239], v[238:239], v[242:243]
	v_pk_mul_f32 v[240:241], v[240:241], v[244:245]
	v_pk_mul_f32 v[32:33], v[32:33], v[238:239]
	v_pk_mul_f32 v[34:35], v[34:35], v[240:241]
	ds_read_u16 v214, v2 offset:16992
	ds_read_u16 v215, v2 offset:17520
	ds_read_u16 v216, v2 offset:18048
	ds_read_u16 v217, v2 offset:18576
	ds_read_u16 v218, v2 offset:19104
	ds_read_u16 v219, v2 offset:19632
	s_waitcnt lgkmcnt(6)
; DI float bf2f(u16 h) { return __uint_as_float(((unsigned)h) << 16); }
; DI float gelu_tanh(float x) { float u = 0.7978845608028654f * (x + 0.044715f * x * x * x); return x * sigmoidf_(2.f * u); }
; DI void ffup_tile(const Params& p, int l, int mt, int nt, char* smem) {
;     ...
; #pragma unroll
;     for (int n = 0; n < 4; ++n) {
;       const int col = col0 + wc * 64 + n * 16 + fr;
;       const float* cw = p.in[30] + (size_t)l * 3 * DFF + col;
;       const float w0 = cw[0], w1 = cw[DFF], w2 = cw[2 * DFF], cb = p.in[31][(size_t)l * DFF + col];
; #pragma unroll
;       for (int m = 0; m < 8; ++m) {
;         if ((m & 1) == 0) asm volatile("" ::: "memory");
;         const int t = (row0 + wr * 128 + m * 16 + fq * 4) & 8191;
;         float g[6];
; #pragma unroll
;         for (int d = 0; d < 6; ++d) { const float gv = bf2f(img[(m * 16 + d) * IMG_LD + n * 16]); g[d] = (d >= 2 || t - 2 + d >= 0) ? gv : 0.f; }
; #pragma unroll
;         for (int j = 0; j < 4; ++j) acc[m][n][j] *= gelu_tanh(cb + w0 * g[j] + w1 * g[j + 1] + w2 * g[j + 2]);
;       }
	v_lshlrev_b32_e32 v226, 16, v226
	v_lshlrev_b32_e32 v227, 16, v227
	v_lshlrev_b32_e32 v228, 16, v228
	v_lshlrev_b32_e32 v229, 16, v229
	v_lshlrev_b32_e32 v230, 16, v230
	v_lshlrev_b32_e32 v231, 16, v231
	v_mov_b32_e32 v232, v227
	v_mov_b32_e32 v233, v228
	v_mov_b32_e32 v234, v229
	v_mov_b32_e32 v235, v230
	v_mov_b32_e32 v236, v231
	v_pk_fma_f32 v[238:239], v[162:163], v[226:227], v[168:169]
	v_pk_fma_f32 v[240:241], v[162:163], v[228:229], v[168:169]
	v_pk_fma_f32 v[238:239], v[164:165], v[232:233], v[238:239]
	v_pk_fma_f32 v[240:241], v[164:165], v[234:235], v[240:241]
	v_pk_fma_f32 v[238:239], v[166:167], v[228:229], v[238:239]
	v_pk_fma_f32 v[240:241], v[166:167], v[230:231], v[240:241]
	v_pk_mul_f32 v[242:243], v[176:177], v[238:239]
	v_pk_mul_f32 v[244:245], v[176:177], v[240:241]
	v_pk_mul_f32 v[242:243], v[238:239], v[242:243]
	v_pk_mul_f32 v[244:245], v[240:241], v[244:245]
	v_pk_fma_f32 v[242:243], v[238:239], v[242:243], v[238:239]
	v_pk_fma_f32 v[244:245], v[240:241], v[244:245], v[240:241]
	v_pk_mul_f32 v[242:243], v[178:179], v[242:243]
	v_pk_mul_f32 v[244:245], v[178:179], v[244:245]
	v_pk_add_f32 v[242:243], v[242:243], v[242:243]
	v_pk_add_f32 v[244:245], v[244:245], v[244:245]
	v_pk_mul_f32 v[242:243], v[180:181], v[242:243]
	v_pk_mul_f32 v[244:245], v[180:181], v[244:245]
	v_exp_f32_e32 v242, v242
	v_exp_f32_e32 v243, v243
	v_exp_f32_e32 v244, v244
	v_exp_f32_e32 v245, v245
	v_pk_add_f32 v[242:243], v[182:183], v[242:243]
	v_pk_add_f32 v[244:245], v[182:183], v[244:245]
	v_rcp_f32_e32 v242, v242
	v_rcp_f32_e32 v243, v243
	v_rcp_f32_e32 v244, v244
	v_rcp_f32_e32 v245, v245
	v_pk_mul_f32 v[238:239], v[238:239], v[242:243]
	v_pk_mul_f32 v[240:241], v[240:241], v[244:245]
	v_pk_mul_f32 v[28:29], v[28:29], v[238:239]
	v_pk_mul_f32 v[30:31], v[30:31], v[240:241]
	ds_read_u16 v226, v2 offset:25440
	ds_read_u16 v227, v2 offset:25968
	ds_read_u16 v228, v2 offset:26496
	ds_read_u16 v229, v2 offset:27024
	ds_read_u16 v230, v2 offset:27552
	ds_read_u16 v231, v2 offset:28080
	s_waitcnt lgkmcnt(6)
	v_lshlrev_b32_e32 v214, 16, v214
	v_lshlrev_b32_e32 v215, 16, v215
	v_lshlrev_b32_e32 v216, 16, v216
	v_lshlrev_b32_e32 v217, 16, v217
	v_lshlrev_b32_e32 v218, 16, v218
	v_lshlrev_b32_e32 v219, 16, v219
	v_mov_b32_e32 v220, v215
	v_mov_b32_e32 v221, v216
	v_mov_b32_e32 v222, v217
	v_mov_b32_e32 v223, v218
	v_mov_b32_e32 v224, v219
	v_pk_fma_f32 v[238:239], v[162:163], v[214:215], v[168:169]
	v_pk_fma_f32 v[240:241], v[162:163], v[216:217], v[168:169]
	v_pk_fma_f32 v[238:239], v[164:165], v[220:221], v[238:239]
	v_pk_fma_f32 v[240:241], v[164:165], v[222:223], v[240:241]
	v_pk_fma_f32 v[238:239], v[166:167], v[216:217], v[238:239]
	v_pk_fma_f32 v[240:241], v[166:167], v[218:219], v[240:241]
	v_pk_mul_f32 v[242:243], v[176:177], v[238:239]
	v_pk_mul_f32 v[244:245], v[176:177], v[240:241]
	v_pk_mul_f32 v[242:243], v[238:239], v[242:243]
	v_pk_mul_f32 v[244:245], v[240:241], v[244:245]
	v_pk_fma_f32 v[242:243], v[238:239], v[242:243], v[238:239]
	v_pk_fma_f32 v[244:245], v[240:241], v[244:245], v[240:241]
	v_pk_mul_f32 v[242:243], v[178:179], v[242:243]
	v_pk_mul_f32 v[244:245], v[178:179], v[244:245]
	v_pk_add_f32 v[242:243], v[242:243], v[242:243]
	v_pk_add_f32 v[244:245], v[244:245], v[244:245]
	v_pk_mul_f32 v[242:243], v[180:181], v[242:243]
	v_pk_mul_f32 v[244:245], v[180:181], v[244:245]
	v_exp_f32_e32 v242, v242
	v_exp_f32_e32 v243, v243
	v_exp_f32_e32 v244, v244
	v_exp_f32_e32 v245, v245
	v_pk_add_f32 v[242:243], v[182:183], v[242:243]
	v_pk_add_f32 v[244:245], v[182:183], v[244:245]
	v_rcp_f32_e32 v242, v242
	v_rcp_f32_e32 v243, v243
	v_rcp_f32_e32 v244, v244
	v_rcp_f32_e32 v245, v245
	v_pk_mul_f32 v[238:239], v[238:239], v[242:243]
	v_pk_mul_f32 v[240:241], v[240:241], v[244:245]
	v_pk_mul_f32 v[24:25], v[24:25], v[238:239]
	v_pk_mul_f32 v[26:27], v[26:27], v[240:241]
	ds_read_u16 v214, v2 offset:33888
	ds_read_u16 v215, v2 offset:34416
	ds_read_u16 v216, v2 offset:34944
	ds_read_u16 v217, v2 offset:35472
	ds_read_u16 v218, v2 offset:36000
	ds_read_u16 v219, v2 offset:36528
	s_waitcnt lgkmcnt(6)
	v_lshlrev_b32_e32 v226, 16, v226
	v_lshlrev_b32_e32 v227, 16, v227
	v_lshlrev_b32_e32 v228, 16, v228
	v_lshlrev_b32_e32 v229, 16, v229
	v_lshlrev_b32_e32 v230, 16, v230
	v_lshlrev_b32_e32 v231, 16, v231
	v_mov_b32_e32 v232, v227
	v_mov_b32_e32 v233, v228
	v_mov_b32_e32 v234, v229
	v_mov_b32_e32 v235, v230
	v_mov_b32_e32 v236, v231
	v_pk_fma_f32 v[238:239], v[162:163], v[226:227], v[168:169]
	v_pk_fma_f32 v[240:241], v[162:163], v[228:229], v[168:169]
	v_pk_fma_f32 v[238:239], v[164:165], v[232:233], v[238:239]
	v_pk_fma_f32 v[240:241], v[164:165], v[234:235], v[240:241]
	v_pk_fma_f32 v[238:239], v[166:167], v[228:229], v[238:239]
	v_pk_fma_f32 v[240:241], v[166:167], v[230:231], v[240:241]
	v_pk_mul_f32 v[242:243], v[176:177], v[238:239]
	v_pk_mul_f32 v[244:245], v[176:177], v[240:241]
	v_pk_mul_f32 v[242:243], v[238:239], v[242:243]
	v_pk_mul_f32 v[244:245], v[240:241], v[244:245]
	v_pk_fma_f32 v[242:243], v[238:239], v[242:243], v[238:239]
	v_pk_fma_f32 v[244:245], v[240:241], v[244:245], v[240:241]
	v_pk_mul_f32 v[242:243], v[178:179], v[242:243]
	v_pk_mul_f32 v[244:245], v[178:179], v[244:245]
	v_pk_add_f32 v[242:243], v[242:243], v[242:243]
	v_pk_add_f32 v[244:245], v[244:245], v[244:245]
	v_pk_mul_f32 v[242:243], v[180:181], v[242:243]
	v_pk_mul_f32 v[244:245], v[180:181], v[244:245]
	v_exp_f32_e32 v242, v242
	v_exp_f32_e32 v243, v243
	v_exp_f32_e32 v244, v244
	v_exp_f32_e32 v245, v245
	v_pk_add_f32 v[242:243], v[182:183], v[242:243]
	v_pk_add_f32 v[244:245], v[182:183], v[244:245]
	v_rcp_f32_e32 v242, v242
	v_rcp_f32_e32 v243, v243
	v_rcp_f32_e32 v244, v244
	v_rcp_f32_e32 v245, v245
	v_pk_mul_f32 v[238:239], v[238:239], v[242:243]
	v_pk_mul_f32 v[240:241], v[240:241], v[244:245]
	v_pk_mul_f32 v[20:21], v[20:21], v[238:239]
	v_pk_mul_f32 v[22:23], v[22:23], v[240:241]
	ds_read_u16 v226, v2 offset:42336
	ds_read_u16 v227, v2 offset:42864
	ds_read_u16 v228, v2 offset:43392
	ds_read_u16 v229, v2 offset:43920
	ds_read_u16 v230, v2 offset:44448
	ds_read_u16 v231, v2 offset:44976
	s_waitcnt lgkmcnt(6)
; DI float bf2f(u16 h) { return __uint_as_float(((unsigned)h) << 16); }
; DI float gelu_tanh(float x) { float u = 0.7978845608028654f * (x + 0.044715f * x * x * x); return x * sigmoidf_(2.f * u); }
; DI void ffup_tile(const Params& p, int l, int mt, int nt, char* smem) {
;     ...
; #pragma unroll
;     for (int n = 0; n < 4; ++n) {
;       const int col = col0 + wc * 64 + n * 16 + fr;
;       const float* cw = p.in[30] + (size_t)l * 3 * DFF + col;
;       const float w0 = cw[0], w1 = cw[DFF], w2 = cw[2 * DFF], cb = p.in[31][(size_t)l * DFF + col];
; #pragma unroll
;       for (int m = 0; m < 8; ++m) {
;         if ((m & 1) == 0) asm volatile("" ::: "memory");
;         const int t = (row0 + wr * 128 + m * 16 + fq * 4) & 8191;
;         float g[6];
; #pragma unroll
;         for (int d = 0; d < 6; ++d) { const float gv = bf2f(img[(m * 16 + d) * IMG_LD + n * 16]); g[d] = (d >= 2 || t - 2 + d >= 0) ? gv : 0.f; }
; #pragma unroll
;         for (int j = 0; j < 4; ++j) acc[m][n][j] *= gelu_tanh(cb + w0 * g[j] + w1 * g[j + 1] + w2 * g[j + 2]);
;       }
	v_lshlrev_b32_e32 v214, 16, v214
	v_lshlrev_b32_e32 v215, 16, v215
	v_lshlrev_b32_e32 v216, 16, v216
	v_lshlrev_b32_e32 v217, 16, v217
	v_lshlrev_b32_e32 v218, 16, v218
	v_lshlrev_b32_e32 v219, 16, v219
	v_mov_b32_e32 v220, v215
	v_mov_b32_e32 v221, v216
	v_mov_b32_e32 v222, v217
	v_mov_b32_e32 v223, v218
	v_mov_b32_e32 v224, v219
	v_pk_fma_f32 v[238:239], v[162:163], v[214:215], v[168:169]
	v_pk_fma_f32 v[240:241], v[162:163], v[216:217], v[168:169]
	v_pk_fma_f32 v[238:239], v[164:165], v[220:221], v[238:239]
	v_pk_fma_f32 v[240:241], v[164:165], v[222:223], v[240:241]
	v_pk_fma_f32 v[238:239], v[166:167], v[216:217], v[238:239]
	v_pk_fma_f32 v[240:241], v[166:167], v[218:219], v[240:241]
	v_pk_mul_f32 v[242:243], v[176:177], v[238:239]
	v_pk_mul_f32 v[244:245], v[176:177], v[240:241]
	v_pk_mul_f32 v[242:243], v[238:239], v[242:243]
	v_pk_mul_f32 v[244:245], v[240:241], v[244:245]
	v_pk_fma_f32 v[242:243], v[238:239], v[242:243], v[238:239]
	v_pk_fma_f32 v[244:245], v[240:241], v[244:245], v[240:241]
	v_pk_mul_f32 v[242:243], v[178:179], v[242:243]
	v_pk_mul_f32 v[244:245], v[178:179], v[244:245]
	v_pk_add_f32 v[242:243], v[242:243], v[242:243]
	v_pk_add_f32 v[244:245], v[244:245], v[244:245]
	v_pk_mul_f32 v[242:243], v[180:181], v[242:243]
	v_pk_mul_f32 v[244:245], v[180:181], v[244:245]
	v_exp_f32_e32 v242, v242
	v_exp_f32_e32 v243, v243
	v_exp_f32_e32 v244, v244
	v_exp_f32_e32 v245, v245
	v_pk_add_f32 v[242:243], v[182:183], v[242:243]
	v_pk_add_f32 v[244:245], v[182:183], v[244:245]
	v_rcp_f32_e32 v242, v242
	v_rcp_f32_e32 v243, v243
	v_rcp_f32_e32 v244, v244
	v_rcp_f32_e32 v245, v245
	v_pk_mul_f32 v[238:239], v[238:239], v[242:243]
	v_pk_mul_f32 v[240:241], v[240:241], v[244:245]
	v_pk_mul_f32 v[16:17], v[16:17], v[238:239]
	v_pk_mul_f32 v[18:19], v[18:19], v[240:241]
	ds_read_u16 v214, v2 offset:50784
	ds_read_u16 v215, v2 offset:51312
	ds_read_u16 v216, v2 offset:51840
	ds_read_u16 v217, v2 offset:52368
	ds_read_u16 v218, v2 offset:52896
	ds_read_u16 v219, v2 offset:53424
	s_waitcnt lgkmcnt(6)
	v_lshlrev_b32_e32 v226, 16, v226
	v_lshlrev_b32_e32 v227, 16, v227
	v_lshlrev_b32_e32 v228, 16, v228
	v_lshlrev_b32_e32 v229, 16, v229
	v_lshlrev_b32_e32 v230, 16, v230
	v_lshlrev_b32_e32 v231, 16, v231
	v_mov_b32_e32 v232, v227
	v_mov_b32_e32 v233, v228
	v_mov_b32_e32 v234, v229
	v_mov_b32_e32 v235, v230
	v_mov_b32_e32 v236, v231
	v_pk_fma_f32 v[238:239], v[162:163], v[226:227], v[168:169]
	v_pk_fma_f32 v[240:241], v[162:163], v[228:229], v[168:169]
	v_pk_fma_f32 v[238:239], v[164:165], v[232:233], v[238:239]
	v_pk_fma_f32 v[240:241], v[164:165], v[234:235], v[240:241]
	v_pk_fma_f32 v[238:239], v[166:167], v[228:229], v[238:239]
	v_pk_fma_f32 v[240:241], v[166:167], v[230:231], v[240:241]
	v_pk_mul_f32 v[242:243], v[176:177], v[238:239]
	v_pk_mul_f32 v[244:245], v[176:177], v[240:241]
	v_pk_mul_f32 v[242:243], v[238:239], v[242:243]
	v_pk_mul_f32 v[244:245], v[240:241], v[244:245]
	v_pk_fma_f32 v[242:243], v[238:239], v[242:243], v[238:239]
	v_pk_fma_f32 v[244:245], v[240:241], v[244:245], v[240:241]
	v_pk_mul_f32 v[242:243], v[178:179], v[242:243]
	v_pk_mul_f32 v[244:245], v[178:179], v[244:245]
	v_pk_add_f32 v[242:243], v[242:243], v[242:243]
	v_pk_add_f32 v[244:245], v[244:245], v[244:245]
	v_pk_mul_f32 v[242:243], v[180:181], v[242:243]
	v_pk_mul_f32 v[244:245], v[180:181], v[244:245]
	v_exp_f32_e32 v242, v242
	v_exp_f32_e32 v243, v243
	v_exp_f32_e32 v244, v244
	v_exp_f32_e32 v245, v245
	v_pk_add_f32 v[242:243], v[182:183], v[242:243]
	v_pk_add_f32 v[244:245], v[182:183], v[244:245]
	v_rcp_f32_e32 v242, v242
	v_rcp_f32_e32 v243, v243
	v_rcp_f32_e32 v244, v244
	v_rcp_f32_e32 v245, v245
	v_pk_mul_f32 v[238:239], v[238:239], v[242:243]
	v_pk_mul_f32 v[240:241], v[240:241], v[244:245]
	v_pk_mul_f32 v[12:13], v[12:13], v[238:239]
	v_pk_mul_f32 v[14:15], v[14:15], v[240:241]
	ds_read_u16 v226, v2 offset:59232
	ds_read_u16 v227, v2 offset:59760
	ds_read_u16 v228, v2 offset:60288
	ds_read_u16 v229, v2 offset:60816
	ds_read_u16 v230, v2 offset:61344
	ds_read_u16 v231, v2 offset:61872
	s_waitcnt lgkmcnt(6)
	v_lshlrev_b32_e32 v214, 16, v214
	v_lshlrev_b32_e32 v215, 16, v215
	v_lshlrev_b32_e32 v216, 16, v216
	v_lshlrev_b32_e32 v217, 16, v217
	v_lshlrev_b32_e32 v218, 16, v218
	v_lshlrev_b32_e32 v219, 16, v219
	v_mov_b32_e32 v220, v215
	v_mov_b32_e32 v221, v216
	v_mov_b32_e32 v222, v217
	v_mov_b32_e32 v223, v218
	v_mov_b32_e32 v224, v219
	v_pk_fma_f32 v[238:239], v[162:163], v[214:215], v[168:169]
	v_pk_fma_f32 v[240:241], v[162:163], v[216:217], v[168:169]
	v_pk_fma_f32 v[238:239], v[164:165], v[220:221], v[238:239]
	v_pk_fma_f32 v[240:241], v[164:165], v[222:223], v[240:241]
	v_pk_fma_f32 v[238:239], v[166:167], v[216:217], v[238:239]
	v_pk_fma_f32 v[240:241], v[166:167], v[218:219], v[240:241]
	v_pk_mul_f32 v[242:243], v[176:177], v[238:239]
	v_pk_mul_f32 v[244:245], v[176:177], v[240:241]
	v_pk_mul_f32 v[242:243], v[238:239], v[242:243]
	v_pk_mul_f32 v[244:245], v[240:241], v[244:245]
	v_pk_fma_f32 v[242:243], v[238:239], v[242:243], v[238:239]
	v_pk_fma_f32 v[244:245], v[240:241], v[244:245], v[240:241]
	v_pk_mul_f32 v[242:243], v[178:179], v[242:243]
	v_pk_mul_f32 v[244:245], v[178:179], v[244:245]
	v_pk_add_f32 v[242:243], v[242:243], v[242:243]
	v_pk_add_f32 v[244:245], v[244:245], v[244:245]
	v_pk_mul_f32 v[242:243], v[180:181], v[242:243]
	v_pk_mul_f32 v[244:245], v[180:181], v[244:245]
	v_exp_f32_e32 v242, v242
	v_exp_f32_e32 v243, v243
	v_exp_f32_e32 v244, v244
	v_exp_f32_e32 v245, v245
	v_pk_add_f32 v[242:243], v[182:183], v[242:243]
	v_pk_add_f32 v[244:245], v[182:183], v[244:245]
	v_rcp_f32_e32 v242, v242
	v_rcp_f32_e32 v243, v243
	v_rcp_f32_e32 v244, v244
	v_rcp_f32_e32 v245, v245
	v_pk_mul_f32 v[238:239], v[238:239], v[242:243]
	v_pk_mul_f32 v[240:241], v[240:241], v[244:245]
	v_pk_mul_f32 v[8:9], v[8:9], v[238:239]
	v_pk_mul_f32 v[10:11], v[10:11], v[240:241]
	s_waitcnt lgkmcnt(0)
; DI float bf2f(u16 h) { return __uint_as_float(((unsigned)h) << 16); }
; DI float gelu_tanh(float x) { float u = 0.7978845608028654f * (x + 0.044715f * x * x * x); return x * sigmoidf_(2.f * u); }
; DI void img_barrier() { asm volatile("s_waitcnt lgkmcnt(0)" ::: "memory"); __builtin_amdgcn_s_barrier(); }
; template <bool ROPE>
; DI void img_put_bf16(const f32x4 (&acc)[8][4], char* smem, int rowoff, float scale, int prow0, const float* cosT) {
;     ...
;   u16* img = (u16*)smem + (wr * 128 + fq * 4 + rowoff) * IMG_LD + wc * 64 + fr;
; #pragma unroll
;   for (int m = 0; m < 8; ++m) {
;     float cs4[4] = {0.f, 0.f, 0.f, 0.f}, sn4[4] = {0.f, 0.f, 0.f, 0.f};
;     if (ROPE) {
; #pragma unroll
;       for (int j = 0; j < 4; ++j) { const int pos = prow0 + wr * 128 + m * 16 + fq * 4 + j; cs4[j] = cosT[pos * 8 + (fr & 7)]; sn4[j] = cosT[8192 * 8 + pos * 8 + (fr & 7)]; }
;     }
; #pragma unroll
;     for (int n = 0; n < 4; ++n)
; #pragma unroll
;       for (int j = 0; j < 4; ++j) img[(m * 16 + j) * IMG_LD + n * 16] = f2bf(epi_val<ROPE>(acc, m, n, j, cs4, sn4, fr) * scale);
; DI void ffup_tile(const Params& p, int l, int mt, int nt, char* smem) {
;     ...
;       for (int m = 0; m < 8; ++m) {
;         if ((m & 1) == 0) asm volatile("" ::: "memory");
;         const int t = (row0 + wr * 128 + m * 16 + fq * 4) & 8191;
;         float g[6];
; #pragma unroll
;         for (int d = 0; d < 6; ++d) { const float gv = bf2f(img[(m * 16 + d) * IMG_LD + n * 16]); g[d] = (d >= 2 || t - 2 + d >= 0) ? gv : 0.f; }
; #pragma unroll
;         for (int j = 0; j < 4; ++j) acc[m][n][j] *= gelu_tanh(cb + w0 * g[j] + w1 * g[j + 1] + w2 * g[j + 2]);
;       }
;     }
;     img_barrier();
;     img_put_bf16<false>(acc, smem, 2, 1.f, 0, nullptr);
	v_lshlrev_b32_e32 v226, 16, v226
	v_lshlrev_b32_e32 v227, 16, v227
	v_lshlrev_b32_e32 v228, 16, v228
	v_lshlrev_b32_e32 v229, 16, v229
	v_lshlrev_b32_e32 v230, 16, v230
	v_lshlrev_b32_e32 v231, 16, v231
	v_mov_b32_e32 v232, v227
	v_mov_b32_e32 v233, v228
	v_mov_b32_e32 v234, v229
	v_mov_b32_e32 v235, v230
	v_mov_b32_e32 v236, v231
	v_pk_fma_f32 v[238:239], v[162:163], v[226:227], v[168:169]
	v_pk_fma_f32 v[240:241], v[162:163], v[228:229], v[168:169]
	v_pk_fma_f32 v[238:239], v[164:165], v[232:233], v[238:239]
	v_pk_fma_f32 v[240:241], v[164:165], v[234:235], v[240:241]
	v_pk_fma_f32 v[238:239], v[166:167], v[228:229], v[238:239]
	v_pk_fma_f32 v[240:241], v[166:167], v[230:231], v[240:241]
	v_pk_mul_f32 v[242:243], v[176:177], v[238:239]
	v_pk_mul_f32 v[244:245], v[176:177], v[240:241]
	v_pk_mul_f32 v[242:243], v[238:239], v[242:243]
	v_pk_mul_f32 v[244:245], v[240:241], v[244:245]
	v_pk_fma_f32 v[242:243], v[238:239], v[242:243], v[238:239]
	v_pk_fma_f32 v[244:245], v[240:241], v[244:245], v[240:241]
	v_pk_mul_f32 v[242:243], v[178:179], v[242:243]
	v_pk_mul_f32 v[244:245], v[178:179], v[244:245]
	v_pk_add_f32 v[242:243], v[242:243], v[242:243]
	v_pk_add_f32 v[244:245], v[244:245], v[244:245]
	v_pk_mul_f32 v[242:243], v[180:181], v[242:243]
	v_pk_mul_f32 v[244:245], v[180:181], v[244:245]
	v_exp_f32_e32 v242, v242
	v_exp_f32_e32 v243, v243
	v_exp_f32_e32 v244, v244
	v_exp_f32_e32 v245, v245
	v_pk_add_f32 v[242:243], v[182:183], v[242:243]
	v_pk_add_f32 v[244:245], v[182:183], v[244:245]
	v_rcp_f32_e32 v242, v242
	v_rcp_f32_e32 v243, v243
	v_rcp_f32_e32 v244, v244
	v_rcp_f32_e32 v245, v245
	v_pk_mul_f32 v[238:239], v[238:239], v[242:243]
	v_pk_mul_f32 v[240:241], v[240:241], v[244:245]
	v_pk_mul_f32 v[4:5], v[4:5], v[238:239]
	v_pk_mul_f32 v[6:7], v[6:7], v[240:241]
	s_waitcnt lgkmcnt(0)
	s_barrier
	v_cvt_pk_bf16_f32 v1, v32, s0
	v_mov_b32_e32 v32, v33
	v_mov_b32_e32 v33, v34
	v_mov_b32_e32 v34, v35
	v_mov_b32_e32 v0, v7
	v_mov_b32_e32 v2, v184
	v_and_b32_e32 v7, 0xc0, v2
	v_and_b32_e32 v35, 15, v2
	v_lshrrev_b32_e32 v132, 1, v2
	v_lshrrev_b32_e32 v2, 2, v2
	v_and_b32_e32 v2, 12, v2
	v_and_or_b32 v2, v132, s5, v2
	v_mul_lo_u32 v2, v2, s3
	v_add_u32_e32 v2, 16, v2
	v_lshlrev_b32_e32 v7, 1, v7
	v_lshlrev_b32_e32 v35, 1, v35
	v_add3_u32 v2, v2, v7, v35
	ds_write_b16 v2, v1 offset:1152
	v_cvt_pk_bf16_f32 v1, v32, s0
	ds_write_b16 v2, v1 offset:1680
	v_cvt_pk_bf16_f32 v1, v33, s0
	ds_write_b16 v2, v1 offset:2208
	v_cvt_pk_bf16_f32 v1, v34, s0
	ds_write_b16 v2, v1 offset:2736
	v_cvt_pk_bf16_f32 v1, v124, s0
	ds_write_b16 v2, v1 offset:9504
	v_cvt_pk_bf16_f32 v1, v125, s0
	ds_write_b16 v2, v1 offset:10032
	v_cvt_pk_bf16_f32 v1, v126, s0
	ds_write_b16 v2, v1 offset:10560
	v_cvt_pk_bf16_f32 v1, v127, s0
	ds_write_b16 v2, v1 offset:11088
	v_cvt_pk_bf16_f32 v1, v92, s0
	ds_write_b16 v2, v1 offset:9536
	v_cvt_pk_bf16_f32 v1, v93, s0
	ds_write_b16 v2, v1 offset:10064
	v_cvt_pk_bf16_f32 v1, v94, s0
	ds_write_b16 v2, v1 offset:10592
	v_cvt_pk_bf16_f32 v1, v95, s0
	ds_write_b16 v2, v1 offset:11120
	v_cvt_pk_bf16_f32 v1, v60, s0
	ds_write_b16 v2, v1 offset:9568
	v_cvt_pk_bf16_f32 v1, v61, s0
	ds_write_b16 v2, v1 offset:10096
	v_cvt_pk_bf16_f32 v1, v62, s0
	ds_write_b16 v2, v1 offset:10624
	v_cvt_pk_bf16_f32 v1, v63, s0
	ds_write_b16 v2, v1 offset:11152
	v_cvt_pk_bf16_f32 v1, v28, s0
	ds_write_b16 v2, v1 offset:9600
	v_cvt_pk_bf16_f32 v1, v29, s0
	ds_write_b16 v2, v1 offset:10128
	v_cvt_pk_bf16_f32 v1, v30, s0
	ds_write_b16 v2, v1 offset:10656
	v_cvt_pk_bf16_f32 v1, v31, s0
	ds_write_b16 v2, v1 offset:11184
	v_cvt_pk_bf16_f32 v1, v120, s0
	ds_write_b16 v2, v1 offset:17952
	v_cvt_pk_bf16_f32 v1, v121, s0
	ds_write_b16 v2, v1 offset:18480
	v_cvt_pk_bf16_f32 v1, v122, s0
	ds_write_b16 v2, v1 offset:19008
	v_cvt_pk_bf16_f32 v1, v123, s0
	ds_write_b16 v2, v1 offset:19536
	v_cvt_pk_bf16_f32 v1, v88, s0
	ds_write_b16 v2, v1 offset:17984
	v_cvt_pk_bf16_f32 v1, v89, s0
	ds_write_b16 v2, v1 offset:18512
	v_cvt_pk_bf16_f32 v1, v90, s0
	ds_write_b16 v2, v1 offset:19040
	v_cvt_pk_bf16_f32 v1, v91, s0
	ds_write_b16 v2, v1 offset:19568
	v_cvt_pk_bf16_f32 v1, v56, s0
	ds_write_b16 v2, v1 offset:18016
	v_cvt_pk_bf16_f32 v1, v57, s0
	ds_write_b16 v2, v1 offset:18544
	v_cvt_pk_bf16_f32 v1, v58, s0
	ds_write_b16 v2, v1 offset:19072
	v_cvt_pk_bf16_f32 v1, v59, s0
	ds_write_b16 v2, v1 offset:19600
	v_cvt_pk_bf16_f32 v1, v24, s0
	ds_write_b16 v2, v1 offset:18048
	v_cvt_pk_bf16_f32 v1, v25, s0
	ds_write_b16 v2, v1 offset:18576
	v_cvt_pk_bf16_f32 v1, v26, s0
	ds_write_b16 v2, v1 offset:19104
	v_cvt_pk_bf16_f32 v1, v27, s0
	ds_write_b16 v2, v1 offset:19632
	v_cvt_pk_bf16_f32 v1, v116, s0
	ds_write_b16 v2, v1 offset:26400
	v_cvt_pk_bf16_f32 v1, v117, s0
	ds_write_b16 v2, v1 offset:26928
	v_cvt_pk_bf16_f32 v1, v118, s0
	ds_write_b16 v2, v1 offset:27456
	v_cvt_pk_bf16_f32 v1, v119, s0
	ds_write_b16 v2, v1 offset:27984
	v_cvt_pk_bf16_f32 v1, v84, s0
	ds_write_b16 v2, v1 offset:26432
	v_cvt_pk_bf16_f32 v1, v85, s0
	ds_write_b16 v2, v1 offset:26960
	v_cvt_pk_bf16_f32 v1, v86, s0
	ds_write_b16 v2, v1 offset:27488
	v_cvt_pk_bf16_f32 v1, v87, s0
	ds_write_b16 v2, v1 offset:28016
	v_cvt_pk_bf16_f32 v1, v52, s0
	ds_write_b16 v2, v1 offset:26464
	v_cvt_pk_bf16_f32 v1, v53, s0
	ds_write_b16 v2, v1 offset:26992
	v_cvt_pk_bf16_f32 v1, v54, s0
	ds_write_b16 v2, v1 offset:27520
	v_cvt_pk_bf16_f32 v1, v55, s0
	ds_write_b16 v2, v1 offset:28048
	v_cvt_pk_bf16_f32 v1, v20, s0
	ds_write_b16 v2, v1 offset:26496
	v_cvt_pk_bf16_f32 v1, v21, s0
	ds_write_b16 v2, v1 offset:27024
	v_cvt_pk_bf16_f32 v1, v22, s0
	ds_write_b16 v2, v1 offset:27552
	v_cvt_pk_bf16_f32 v1, v23, s0
	ds_write_b16 v2, v1 offset:28080
; template <bool ROPE>
; DI void img_put_bf16(const f32x4 (&acc)[8][4], char* smem, int rowoff, float scale, int prow0, const float* cosT) {
;     ...
;   u16* img = (u16*)smem + (wr * 128 + fq * 4 + rowoff) * IMG_LD + wc * 64 + fr;
; #pragma unroll
;   for (int m = 0; m < 8; ++m) {
;     float cs4[4] = {0.f, 0.f, 0.f, 0.f}, sn4[4] = {0.f, 0.f, 0.f, 0.f};
;     if (ROPE) {
; #pragma unroll
;       for (int j = 0; j < 4; ++j) { const int pos = prow0 + wr * 128 + m * 16 + fq * 4 + j; cs4[j] = cosT[pos * 8 + (fr & 7)]; sn4[j] = cosT[8192 * 8 + pos * 8 + (fr & 7)]; }
;     }
; #pragma unroll
;     for (int n = 0; n < 4; ++n)
; #pragma unroll
;       for (int j = 0; j < 4; ++j) img[(m * 16 + j) * IMG_LD + n * 16] = f2bf(epi_val<ROPE>(acc, m, n, j, cs4, sn4, fr) * scale);
	v_cvt_pk_bf16_f32 v1, v112, s0
	ds_write_b16 v2, v1 offset:34848
	v_cvt_pk_bf16_f32 v1, v113, s0
	ds_write_b16 v2, v1 offset:35376
	v_cvt_pk_bf16_f32 v1, v114, s0
	ds_write_b16 v2, v1 offset:35904
	v_cvt_pk_bf16_f32 v1, v115, s0
	ds_write_b16 v2, v1 offset:36432
	v_cvt_pk_bf16_f32 v1, v80, s0
	ds_write_b16 v2, v1 offset:34880
	v_cvt_pk_bf16_f32 v1, v81, s0
	ds_write_b16 v2, v1 offset:35408
	v_cvt_pk_bf16_f32 v1, v82, s0
	ds_write_b16 v2, v1 offset:35936
	v_cvt_pk_bf16_f32 v1, v83, s0
	ds_write_b16 v2, v1 offset:36464
	v_cvt_pk_bf16_f32 v1, v48, s0
	ds_write_b16 v2, v1 offset:34912
	v_cvt_pk_bf16_f32 v1, v49, s0
	ds_write_b16 v2, v1 offset:35440
	v_cvt_pk_bf16_f32 v1, v50, s0
	ds_write_b16 v2, v1 offset:35968
	v_cvt_pk_bf16_f32 v1, v51, s0
	ds_write_b16 v2, v1 offset:36496
	v_cvt_pk_bf16_f32 v1, v16, s0
	ds_write_b16 v2, v1 offset:34944
	v_cvt_pk_bf16_f32 v1, v17, s0
	ds_write_b16 v2, v1 offset:35472
	v_cvt_pk_bf16_f32 v1, v18, s0
	ds_write_b16 v2, v1 offset:36000
	v_cvt_pk_bf16_f32 v1, v19, s0
	ds_write_b16 v2, v1 offset:36528
	v_cvt_pk_bf16_f32 v1, v108, s0
	ds_write_b16 v2, v1 offset:43296
	v_cvt_pk_bf16_f32 v1, v109, s0
	ds_write_b16 v2, v1 offset:43824
	v_cvt_pk_bf16_f32 v1, v110, s0
	ds_write_b16 v2, v1 offset:44352
	v_cvt_pk_bf16_f32 v1, v111, s0
	ds_write_b16 v2, v1 offset:44880
	v_cvt_pk_bf16_f32 v1, v76, s0
	ds_write_b16 v2, v1 offset:43328
	v_cvt_pk_bf16_f32 v1, v77, s0
	ds_write_b16 v2, v1 offset:43856
	v_cvt_pk_bf16_f32 v1, v78, s0
	ds_write_b16 v2, v1 offset:44384
	v_cvt_pk_bf16_f32 v1, v79, s0
	ds_write_b16 v2, v1 offset:44912
	v_cvt_pk_bf16_f32 v1, v44, s0
	ds_write_b16 v2, v1 offset:43360
	v_cvt_pk_bf16_f32 v1, v45, s0
	ds_write_b16 v2, v1 offset:43888
	v_cvt_pk_bf16_f32 v1, v46, s0
	ds_write_b16 v2, v1 offset:44416
	v_cvt_pk_bf16_f32 v1, v47, s0
	ds_write_b16 v2, v1 offset:44944
	v_cvt_pk_bf16_f32 v1, v12, s0
	ds_write_b16 v2, v1 offset:43392
	v_cvt_pk_bf16_f32 v1, v13, s0
	ds_write_b16 v2, v1 offset:43920
	v_cvt_pk_bf16_f32 v1, v14, s0
	ds_write_b16 v2, v1 offset:44448
	v_cvt_pk_bf16_f32 v1, v15, s0
	ds_write_b16 v2, v1 offset:44976
	v_cvt_pk_bf16_f32 v1, v104, s0
	ds_write_b16 v2, v1 offset:51744
	v_cvt_pk_bf16_f32 v1, v105, s0
	ds_write_b16 v2, v1 offset:52272
	v_cvt_pk_bf16_f32 v1, v106, s0
	ds_write_b16 v2, v1 offset:52800
	v_cvt_pk_bf16_f32 v1, v107, s0
	ds_write_b16 v2, v1 offset:53328
	v_cvt_pk_bf16_f32 v1, v72, s0
	ds_write_b16 v2, v1 offset:51776
	v_cvt_pk_bf16_f32 v1, v73, s0
	ds_write_b16 v2, v1 offset:52304
	v_cvt_pk_bf16_f32 v1, v74, s0
	ds_write_b16 v2, v1 offset:52832
	v_cvt_pk_bf16_f32 v1, v75, s0
	ds_write_b16 v2, v1 offset:53360
	v_cvt_pk_bf16_f32 v1, v40, s0
	ds_write_b16 v2, v1 offset:51808
	v_cvt_pk_bf16_f32 v1, v41, s0
	ds_write_b16 v2, v1 offset:52336
	v_cvt_pk_bf16_f32 v1, v42, s0
	ds_write_b16 v2, v1 offset:52864
	v_cvt_pk_bf16_f32 v1, v43, s0
	ds_write_b16 v2, v1 offset:53392
	v_cvt_pk_bf16_f32 v1, v8, s0
	ds_write_b16 v2, v1 offset:51840
	v_cvt_pk_bf16_f32 v1, v9, s0
	ds_write_b16 v2, v1 offset:52368
	v_cvt_pk_bf16_f32 v1, v10, s0
	ds_write_b16 v2, v1 offset:52896
	v_cvt_pk_bf16_f32 v1, v11, s0
	ds_write_b16 v2, v1 offset:53424
	v_cvt_pk_bf16_f32 v1, v100, s0
	ds_write_b16 v2, v1 offset:60192
	v_cvt_pk_bf16_f32 v1, v101, s0
	ds_write_b16 v2, v1 offset:60720
	v_cvt_pk_bf16_f32 v1, v102, s0
	v_cvt_pk_bf16_f32 v7, v128, s0
	ds_write_b16 v2, v1 offset:61248
	v_cvt_pk_bf16_f32 v1, v103, s0
	ds_write_b16 v2, v7 offset:1056
	v_cvt_pk_bf16_f32 v7, v129, s0
	ds_write_b16 v2, v1 offset:61776
	v_cvt_pk_bf16_f32 v1, v68, s0
	ds_write_b16 v2, v7 offset:1584
	v_cvt_pk_bf16_f32 v7, v130, s0
	ds_write_b16 v2, v1 offset:60224
	v_cvt_pk_bf16_f32 v1, v69, s0
	ds_write_b16 v2, v7 offset:2112
	v_cvt_pk_bf16_f32 v7, v131, s0
	ds_write_b16 v2, v1 offset:60752
	v_cvt_pk_bf16_f32 v1, v70, s0
	ds_write_b16 v2, v7 offset:2640
	v_cvt_pk_bf16_f32 v7, v96, s0
	ds_write_b16 v2, v1 offset:61280
	v_cvt_pk_bf16_f32 v1, v71, s0
	ds_write_b16 v2, v7 offset:1088
	v_cvt_pk_bf16_f32 v7, v97, s0
	ds_write_b16 v2, v1 offset:61808
	v_cvt_pk_bf16_f32 v1, v36, s0
	ds_write_b16 v2, v7 offset:1616
	v_cvt_pk_bf16_f32 v7, v98, s0
	ds_write_b16 v2, v1 offset:60256
	v_cvt_pk_bf16_f32 v1, v37, s0
	ds_write_b16 v2, v7 offset:2144
	v_cvt_pk_bf16_f32 v7, v99, s0
	ds_write_b16 v2, v1 offset:60784
	v_cvt_pk_bf16_f32 v1, v38, s0
	ds_write_b16 v2, v7 offset:2672
	v_cvt_pk_bf16_f32 v7, v64, s0
	ds_write_b16 v2, v1 offset:61312
	v_cvt_pk_bf16_f32 v1, v39, s0
	ds_write_b16 v2, v7 offset:1120
	v_cvt_pk_bf16_f32 v7, v65, s0
	ds_write_b16 v2, v1 offset:61840
	v_cvt_pk_bf16_f32 v1, v4, s0
	ds_write_b16 v2, v7 offset:1648
	v_cvt_pk_bf16_f32 v7, v66, s0
	ds_write_b16 v2, v1 offset:60288
	v_cvt_pk_bf16_f32 v1, v5, s0
	ds_write_b16 v2, v7 offset:2176
	v_cvt_pk_bf16_f32 v7, v67, s0
	ds_write_b16 v2, v1 offset:60816
	v_cvt_pk_bf16_f32 v1, v6, s0
	v_cvt_pk_bf16_f32 v0, v0, s0
	ds_write_b16 v2, v7 offset:2704
	ds_write_b16 v2, v1 offset:61344
	ds_write_b16 v2, v0 offset:61872
	v_mov_b32_e32 v1, v184
	s_waitcnt lgkmcnt(0)
	s_barrier
; DI int TID512() { int t = threadIdx.x; asm volatile("" : "+v"(t)); return t; }
; DI void img_store_bf16(u16* dst, int ld, const char* smem, int rowoff) {
;   const int tid = TID512();
; #pragma unroll
;   for (int q = 0; q < 16; ++q) {
;     const int slot = tid + q * 512, row = slot >> 5, c16 = slot & 31;
;     *(u32x4*)(dst + (size_t)row * ld + c16 * 8) = *(const u32x4*)(smem + (row + rowoff) * (IMG_LD * 2) + c16 * 16);
;   }
; }
	s_addc_u32 s5, s77, s39
	s_add_u32 s4, s4, s48
	v_lshlrev_b32_e32 v0, 4, v1
	v_and_b32_e32 v172, 0x1f0, v0
	s_addc_u32 s5, s5, s49
	v_add_u32_e32 v0, 16, v172
	v_ashrrev_i32_e32 v2, 5, v1
	v_lshl_add_u64 v[8:9], s[4:5], 0, v[172:173]
	v_mad_u64_u32 v[4:5], s[4:5], v2, s3, v[0:1]
	ds_read_b128 v[4:7], v4 offset:1056
	v_mad_i64_i32 v[10:11], s[4:5], v2, s96, v[8:9]
	v_add_u32_e32 v2, 0x200, v1
	v_ashrrev_i32_e32 v2, 5, v2
	s_waitcnt lgkmcnt(0)
	global_store_dwordx4 v[10:11], v[4:7], off
	v_mad_i64_i32 v[10:11], s[4:5], v2, s96, v[8:9]
	s_nop 0
	v_mad_u64_u32 v[4:5], s[4:5], v2, s3, v[0:1]
	ds_read_b128 v[4:7], v4 offset:1056
	v_add_u32_e32 v2, 0x400, v1
	v_ashrrev_i32_e32 v2, 5, v2
	s_waitcnt lgkmcnt(0)
	global_store_dwordx4 v[10:11], v[4:7], off
	s_nop 1
	v_mad_u64_u32 v[4:5], s[4:5], v2, s3, v[0:1]
	ds_read_b128 v[4:7], v4 offset:1056
	v_mad_i64_i32 v[10:11], s[4:5], v2, s96, v[8:9]
	v_add_u32_e32 v2, 0x600, v1
	v_ashrrev_i32_e32 v2, 5, v2
	s_waitcnt lgkmcnt(0)
	global_store_dwordx4 v[10:11], v[4:7], off
	v_mad_i64_i32 v[10:11], s[4:5], v2, s96, v[8:9]
	s_nop 0
	v_mad_u64_u32 v[4:5], s[4:5], v2, s3, v[0:1]
	ds_read_b128 v[4:7], v4 offset:1056
	v_add_u32_e32 v2, 0x800, v1
	v_ashrrev_i32_e32 v2, 5, v2
	s_waitcnt lgkmcnt(0)
	global_store_dwordx4 v[10:11], v[4:7], off
	s_nop 1
	v_mad_u64_u32 v[4:5], s[4:5], v2, s3, v[0:1]
	ds_read_b128 v[4:7], v4 offset:1056
	v_mad_i64_i32 v[10:11], s[4:5], v2, s96, v[8:9]
	v_add_u32_e32 v2, 0xa00, v1
	v_ashrrev_i32_e32 v2, 5, v2
	s_waitcnt lgkmcnt(0)
	global_store_dwordx4 v[10:11], v[4:7], off
	v_mad_i64_i32 v[10:11], s[4:5], v2, s96, v[8:9]
	s_nop 0
	v_mad_u64_u32 v[4:5], s[4:5], v2, s3, v[0:1]
	ds_read_b128 v[4:7], v4 offset:1056
	v_add_u32_e32 v2, 0xc00, v1
	v_ashrrev_i32_e32 v2, 5, v2
	s_waitcnt lgkmcnt(0)
	global_store_dwordx4 v[10:11], v[4:7], off
	s_nop 1
	v_mad_u64_u32 v[4:5], s[4:5], v2, s3, v[0:1]
	ds_read_b128 v[4:7], v4 offset:1056
	v_mad_i64_i32 v[10:11], s[4:5], v2, s96, v[8:9]
	v_add_u32_e32 v2, 0xe00, v1
	v_ashrrev_i32_e32 v2, 5, v2
	s_waitcnt lgkmcnt(0)
	global_store_dwordx4 v[10:11], v[4:7], off
	v_mad_i64_i32 v[10:11], s[4:5], v2, s96, v[8:9]
	s_nop 0
	v_mad_u64_u32 v[4:5], s[4:5], v2, s3, v[0:1]
	ds_read_b128 v[4:7], v4 offset:1056
	v_add_u32_e32 v2, 0x1000, v1
	v_ashrrev_i32_e32 v2, 5, v2
	s_waitcnt lgkmcnt(0)
	global_store_dwordx4 v[10:11], v[4:7], off
	s_nop 1
	v_mad_u64_u32 v[4:5], s[4:5], v2, s3, v[0:1]
	ds_read_b128 v[4:7], v4 offset:1056
	v_mad_i64_i32 v[10:11], s[4:5], v2, s96, v[8:9]
	v_add_u32_e32 v2, 0x1200, v1
	v_ashrrev_i32_e32 v2, 5, v2
	s_waitcnt lgkmcnt(0)
	global_store_dwordx4 v[10:11], v[4:7], off
	v_mad_i64_i32 v[10:11], s[4:5], v2, s96, v[8:9]
	s_nop 0
	v_mad_u64_u32 v[4:5], s[4:5], v2, s3, v[0:1]
	ds_read_b128 v[4:7], v4 offset:1056
	v_add_u32_e32 v2, 0x1400, v1
	v_ashrrev_i32_e32 v2, 5, v2
	s_waitcnt lgkmcnt(0)
	global_store_dwordx4 v[10:11], v[4:7], off
	s_nop 1
	v_mad_u64_u32 v[4:5], s[4:5], v2, s3, v[0:1]
	ds_read_b128 v[4:7], v4 offset:1056
	v_mad_i64_i32 v[10:11], s[4:5], v2, s96, v[8:9]
	v_add_u32_e32 v2, 0x1600, v1
	v_ashrrev_i32_e32 v2, 5, v2
	s_waitcnt lgkmcnt(0)
	global_store_dwordx4 v[10:11], v[4:7], off
	v_mad_i64_i32 v[10:11], s[4:5], v2, s96, v[8:9]
	s_nop 0
	v_mad_u64_u32 v[4:5], s[4:5], v2, s3, v[0:1]
	ds_read_b128 v[4:7], v4 offset:1056
	v_add_u32_e32 v2, 0x1800, v1
	v_ashrrev_i32_e32 v2, 5, v2
	s_waitcnt lgkmcnt(0)
	global_store_dwordx4 v[10:11], v[4:7], off
	s_nop 1
	v_mad_u64_u32 v[4:5], s[4:5], v2, s3, v[0:1]
	ds_read_b128 v[4:7], v4 offset:1056
	v_mad_i64_i32 v[10:11], s[4:5], v2, s96, v[8:9]
	v_add_u32_e32 v2, 0x1a00, v1
	v_ashrrev_i32_e32 v2, 5, v2
	s_waitcnt lgkmcnt(0)
	global_store_dwordx4 v[10:11], v[4:7], off
	v_mad_i64_i32 v[10:11], s[4:5], v2, s96, v[8:9]
	s_nop 0
	v_mad_u64_u32 v[4:5], s[4:5], v2, s3, v[0:1]
	ds_read_b128 v[4:7], v4 offset:1056
	v_add_u32_e32 v2, 0x1c00, v1
	v_ashrrev_i32_e32 v2, 5, v2
	s_waitcnt lgkmcnt(0)
	global_store_dwordx4 v[10:11], v[4:7], off
	s_nop 1
	v_mad_u64_u32 v[4:5], s[4:5], v2, s3, v[0:1]
	ds_read_b128 v[4:7], v4 offset:1056
	v_add_u32_e32 v1, 0x1e00, v1
	v_mad_i64_i32 v[10:11], s[4:5], v2, s96, v[8:9]
	v_ashrrev_i32_e32 v2, 5, v1
	v_mad_u64_u32 v[0:1], s[4:5], v2, s3, v[0:1]
	s_waitcnt lgkmcnt(0)
	global_store_dwordx4 v[10:11], v[4:7], off
	ds_read_b128 v[4:7], v0 offset:1056
	v_mad_i64_i32 v[0:1], s[4:5], v2, s96, v[8:9]
	s_waitcnt lgkmcnt(0)
	global_store_dwordx4 v[0:1], v[4:7], off
